# DIFF item epilogue: 28 scratch loads issued together (dead regs) instead of load-wait-unpack chain; item_cmp1 bias sums: 8 loads in flight per loop iteration
# speedup vs baseline: 1.0060x; 1.0060x over previous
.LBB0_498:
	s_mov_b64 s[0:1], -1
	s_and_b64 vcc, exec, s[20:21]
	s_cbranch_vccz .LBB0_500
	v_mov_b32_e32 v2, v222
	v_and_b32_e32 v7, 64, v228
	v_and_b32_e32 v3, 63, v2
	v_lshlrev_b32_e32 v3, 2, v3
	global_load_dword v4, v3, s[8:9]
	global_load_dword v5, v3, s[8:9] offset:256
	v_add_u32_e32 v7, 64, v7
	v_xor_b32_e32 v8, 32, v228
	v_cmp_lt_i32_e32 vcc, v8, v7
	s_movk_i32 s0, 0x3000
	v_mov_b32_e32 v132, v44
	v_cndmask_b32_e32 v8, v228, v8, vcc
	s_waitcnt vmcnt(2)
	v_lshlrev_b32_e32 v166, 2, v8
	v_mov_b32_e32 v133, v42
	v_ashrrev_i32_e32 v0, 1, v2
	v_and_b32_e32 v0, 0xffffffe0, v0
	v_add_u32_e32 v0, s46, v0
	s_waitcnt vmcnt(0)
	v_mul_f32_e32 v6, v4, v5
	ds_bpermute_b32 v6, v166, v6
	s_waitcnt lgkmcnt(0)
	v_fmac_f32_e32 v6, v4, v5
	v_xor_b32_e32 v4, 16, v228
	v_cmp_lt_i32_e32 vcc, v4, v7
	s_nop 1
	v_cndmask_b32_e32 v4, v228, v4, vcc
	v_lshlrev_b32_e32 v4, 2, v4
	ds_bpermute_b32 v5, v4, v6
	s_waitcnt lgkmcnt(0)
	v_add_f32_e32 v5, v6, v5
	v_xor_b32_e32 v6, 8, v228
	v_cmp_lt_i32_e32 vcc, v6, v7
	s_nop 1
	v_cndmask_b32_e32 v6, v228, v6, vcc
	v_lshlrev_b32_e32 v6, 2, v6
	ds_bpermute_b32 v8, v6, v5
	s_waitcnt lgkmcnt(0)
	v_add_f32_e32 v5, v5, v8
	v_xor_b32_e32 v8, 4, v228
	v_cmp_lt_i32_e32 vcc, v8, v7
	s_nop 1
	v_cndmask_b32_e32 v8, v228, v8, vcc
	v_lshlrev_b32_e32 v8, 2, v8
	ds_bpermute_b32 v9, v8, v5
	s_waitcnt lgkmcnt(0)
	v_add_f32_e32 v5, v5, v9
	v_xor_b32_e32 v9, 2, v228
	v_cmp_lt_i32_e32 vcc, v9, v7
	s_nop 1
	v_cndmask_b32_e32 v9, v228, v9, vcc
	v_lshlrev_b32_e32 v9, 2, v9
	ds_bpermute_b32 v10, v9, v5
	s_waitcnt lgkmcnt(0)
	v_add_f32_e32 v5, v5, v10
	v_xor_b32_e32 v10, 1, v228
	v_cmp_lt_i32_e32 vcc, v10, v7
	s_nop 1
	v_cndmask_b32_e32 v7, v228, v10, vcc
	v_lshlrev_b32_e32 v7, 2, v7
	ds_bpermute_b32 v10, v7, v5
	s_waitcnt lgkmcnt(0)
	v_add_f32_e32 v5, v5, v10
	global_load_dword v10, v3, s[8:9] offset:512
	s_nop 0
	global_load_dword v3, v3, s[8:9] offset:768
	s_waitcnt vmcnt(0)
	v_mul_f32_e32 v11, v10, v3
	ds_bpermute_b32 v11, v166, v11
	s_waitcnt lgkmcnt(0)
	v_fmac_f32_e32 v11, v10, v3
	ds_bpermute_b32 v3, v4, v11
	s_waitcnt lgkmcnt(0)
	v_add_f32_e32 v3, v11, v3
	ds_bpermute_b32 v4, v6, v3
	s_waitcnt lgkmcnt(0)
	v_add_f32_e32 v3, v3, v4
	ds_bpermute_b32 v4, v8, v3
	s_waitcnt lgkmcnt(0)
	v_add_f32_e32 v3, v3, v4
	ds_bpermute_b32 v4, v9, v3
	s_waitcnt lgkmcnt(0)
	v_add_f32_e32 v3, v3, v4
	ds_bpermute_b32 v4, v7, v3
	s_waitcnt lgkmcnt(0)
	v_add_f32_e32 v3, v3, v4
	v_mul_f32_e32 v4, 0x3fb8aa3b, v5
	v_mul_f32_e32 v3, 0x3fb8aa3b, v3
	v_exp_f32_e32 v4, v4
	v_exp_f32_e32 v3, v3
	s_nop 0
	v_sub_f32_e32 v3, v4, v3
	ds_bpermute_b32 v4, v166, v203
	v_add_f32_e32 v3, v211, v3
	s_waitcnt lgkmcnt(0)
	v_add_f32_e32 v4, v203, v4
	v_rcp_f32_e32 v4, v4
	s_nop 0
	v_mul_f32_e32 v6, v4, v3
	v_ashrrev_i32_e32 v3, 31, v2
	v_lshl_add_u64 v[4:5], v[2:3], 2, s[10:11]
	global_load_dword v134, v[4:5], off
	v_add_co_u32_e32 v8, vcc, s65, v4
	global_load_dword v135, v[4:5], off offset:1024
	s_nop 1
	v_addc_co_u32_e32 v9, vcc, 0, v5, vcc
	v_add_co_u32_e32 v10, vcc, s57, v4
	global_load_dword v136, v[4:5], off offset:2048
	s_nop 1
	v_addc_co_u32_e32 v11, vcc, 0, v5, vcc
	global_load_dword v137, v[4:5], off offset:3072
	global_load_dword v138, v[10:11], off offset:-4096
	global_load_dword v139, v[8:9], off offset:1024
	global_load_dword v140, v[8:9], off offset:2048
	global_load_dword v141, v[8:9], off offset:3072
	v_add_co_u32_e32 v8, vcc, s0, v4
	s_movk_i32 s0, 0x7000
	s_nop 0
	s_nop 1
	v_addc_co_u32_e32 v9, vcc, 0, v5, vcc
	global_load_dword v142, v[10:11], off
	global_load_dword v143, v[10:11], off offset:1024
	global_load_dword v144, v[10:11], off offset:2048
	global_load_dword v145, v[10:11], off offset:3072
	v_add_co_u32_e32 v10, vcc, s62, v4
	s_nop 1
	v_addc_co_u32_e32 v11, vcc, 0, v5, vcc
	global_load_dword v146, v[10:11], off offset:-4096
	global_load_dword v147, v[8:9], off offset:1024
	global_load_dword v148, v[8:9], off offset:2048
	global_load_dword v149, v[8:9], off offset:3072
	v_add_co_u32_e32 v8, vcc, s64, v4
	global_load_dword v150, v[10:11], off
	s_nop 1
	v_addc_co_u32_e32 v9, vcc, 0, v5, vcc
	global_load_dword v151, v[10:11], off offset:1024
	global_load_dword v152, v[10:11], off offset:2048
	global_load_dword v153, v[10:11], off offset:3072
	v_add_co_u32_e32 v10, vcc, s88, v4
	s_nop 1
	v_addc_co_u32_e32 v11, vcc, 0, v5, vcc
	global_load_dword v154, v[10:11], off offset:-4096
	v_add_co_u32_e32 v4, vcc, s0, v4
	s_mov_b64 s[0:1], 0
	s_nop 0
	s_nop 1
	v_addc_co_u32_e32 v5, vcc, 0, v5, vcc
	global_load_dword v155, v[8:9], off offset:1024
	global_load_dword v156, v[8:9], off offset:2048
	global_load_dword v157, v[8:9], off offset:3072
	global_load_dword v158, v[10:11], off
	global_load_dword v159, v[10:11], off offset:1024
	global_load_dword v160, v[10:11], off offset:2048
	global_load_dword v161, v[10:11], off offset:3072
	s_waitcnt vmcnt(0)
	v_lshlrev_b32_e32 v16, 16, v134
	v_and_b32_e32 v17, 0xffff0000, v134
	v_lshlrev_b32_e32 v30, 16, v135
	v_and_b32_e32 v31, 0xffff0000, v135
	v_lshlrev_b32_e32 v12, 16, v136
	v_and_b32_e32 v13, 0xffff0000, v136
	v_lshlrev_b32_e32 v28, 16, v137
	v_and_b32_e32 v29, 0xffff0000, v137
	v_lshlrev_b32_e32 v26, 16, v138
	v_and_b32_e32 v27, 0xffff0000, v138
	v_lshlrev_b32_e32 v98, 16, v139
	v_and_b32_e32 v99, 0xffff0000, v139
	v_lshlrev_b32_e32 v22, 16, v140
	v_and_b32_e32 v23, 0xffff0000, v140
	v_lshlrev_b32_e32 v32, 16, v141
	v_and_b32_e32 v33, 0xffff0000, v141
	v_lshlrev_b32_e32 v18, 16, v142
	v_and_b32_e32 v19, 0xffff0000, v142
	v_lshlrev_b32_e32 v24, 16, v143
	v_and_b32_e32 v25, 0xffff0000, v143
	v_lshlrev_b32_e32 v14, 16, v144
	v_and_b32_e32 v15, 0xffff0000, v144
	v_lshlrev_b32_e32 v20, 16, v145
	v_and_b32_e32 v21, 0xffff0000, v145
	v_lshlrev_b32_e32 v110, 16, v146
	v_and_b32_e32 v111, 0xffff0000, v146
	v_lshlrev_b32_e32 v114, 16, v147
	v_and_b32_e32 v115, 0xffff0000, v147
	v_lshlrev_b32_e32 v106, 16, v148
	v_and_b32_e32 v107, 0xffff0000, v148
	v_lshlrev_b32_e32 v112, 16, v149
	v_and_b32_e32 v113, 0xffff0000, v149
	v_lshlrev_b32_e32 v102, 16, v150
	v_and_b32_e32 v103, 0xffff0000, v150
	v_lshlrev_b32_e32 v108, 16, v151
	v_and_b32_e32 v109, 0xffff0000, v151
	v_lshlrev_b32_e32 v100, 16, v152
	v_and_b32_e32 v101, 0xffff0000, v152
	v_lshlrev_b32_e32 v104, 16, v153
	v_and_b32_e32 v105, 0xffff0000, v153
	v_lshlrev_b32_e32 v126, 16, v154
	v_and_b32_e32 v127, 0xffff0000, v154
	v_lshlrev_b32_e32 v130, 16, v155
	v_and_b32_e32 v131, 0xffff0000, v155
	v_lshlrev_b32_e32 v124, 16, v156
	v_and_b32_e32 v125, 0xffff0000, v156
	v_lshlrev_b32_e32 v128, 16, v157
	v_and_b32_e32 v129, 0xffff0000, v157
	v_lshlrev_b32_e32 v120, 16, v158
	v_and_b32_e32 v121, 0xffff0000, v158
	v_lshlrev_b32_e32 v122, 16, v159
	v_and_b32_e32 v123, 0xffff0000, v159
	v_lshlrev_b32_e32 v116, 16, v160
	v_and_b32_e32 v117, 0xffff0000, v160
	v_lshlrev_b32_e32 v118, 16, v161
	v_and_b32_e32 v119, 0xffff0000, v161
	global_load_dword v3, v[4:5], off
	global_load_dword v7, v[4:5], off offset:1024
	s_waitcnt vmcnt(1)
	v_lshlrev_b32_e32 v9, 16, v3
	s_waitcnt vmcnt(0)
	v_lshlrev_b32_e32 v8, 16, v7
	v_and_b32_e32 v11, 0xffff0000, v3
	v_and_b32_e32 v10, 0xffff0000, v7
	v_pk_fma_f32 v[8:9], v[132:133], v[6:7], v[8:9] op_sel_hi:[1,0,1] neg_lo:[1,0,0] neg_hi:[1,0,0]
	v_mov_b32_e32 v132, v45
	v_mov_b32_e32 v133, v43
	v_pk_fma_f32 v[10:11], v[132:133], v[6:7], v[10:11] op_sel_hi:[1,0,1] neg_lo:[1,0,0] neg_hi:[1,0,0]
	global_load_dword v3, v[4:5], off offset:2048
	global_load_dword v7, v[4:5], off offset:3072
	v_pk_mul_f32 v[132:133], v[10:11], v[10:11]
	s_waitcnt vmcnt(1)
	v_lshlrev_b32_e32 v5, 16, v3
	v_pk_fma_f32 v[136:137], v[8:9], v[8:9], v[132:133]
	s_waitcnt vmcnt(0)
	v_lshlrev_b32_e32 v4, 16, v7
	v_mov_b32_e32 v132, v48
	v_mov_b32_e32 v133, v46
	v_and_b32_e32 v135, 0xffff0000, v3
	v_and_b32_e32 v134, 0xffff0000, v7
	v_pk_fma_f32 v[132:133], v[132:133], v[6:7], v[4:5] op_sel_hi:[1,0,1] neg_lo:[1,0,0] neg_hi:[1,0,0]
	v_mov_b32_e32 v4, v49
	v_mov_b32_e32 v5, v47
	v_pk_fma_f32 v[134:135], v[4:5], v[6:7], v[134:135] op_sel_hi:[1,0,1] neg_lo:[1,0,0] neg_hi:[1,0,0]
	v_pk_fma_f32 v[144:145], v[68:69], v[6:7], v[24:25] op_sel_hi:[1,0,1] neg_lo:[1,0,0] neg_hi:[1,0,0]
	v_pk_mul_f32 v[4:5], v[134:135], v[134:135]
	v_pk_fma_f32 v[148:149], v[66:67], v[6:7], v[18:19] op_sel_hi:[1,0,1] neg_lo:[1,0,0] neg_hi:[1,0,0]
	v_pk_fma_f32 v[154:155], v[132:133], v[132:133], v[4:5]
	v_and_or_b32 v4, v2, 31, v0
	v_ashrrev_i32_e32 v5, 31, v4
	v_lshrrev_b32_e32 v0, 3, v2
	v_lshl_add_u64 v[4:5], s[60:61], 0, v[4:5]
	v_and_b32_e32 v0, 4, v0
	v_lshlrev_b64 v[4:5], 10, v[4:5]
	v_lshlrev_b32_e32 v167, 2, v0
	v_lshl_add_u64 v[138:139], s[14:15], 0, v[4:5]
	global_load_dwordx4 v[2:5], v167, s[12:13]
	v_pk_fma_f32 v[18:19], v[64:65], v[6:7], v[128:129] op_sel_hi:[1,0,1] neg_lo:[1,0,0] neg_hi:[1,0,0]
	v_pk_fma_f32 v[24:25], v[62:63], v[6:7], v[124:125] op_sel_hi:[1,0,1] neg_lo:[1,0,0] neg_hi:[1,0,0]
	v_pk_fma_f32 v[142:143], v[70:71], v[6:7], v[14:15] op_sel_hi:[1,0,1] neg_lo:[1,0,0] neg_hi:[1,0,0]
	v_mov_b32_e32 v14, v19
	v_mov_b32_e32 v15, v25
	v_lshlrev_b32_e32 v0, 1, v0
	v_pk_fma_f32 v[160:161], v[86:87], v[6:7], v[12:13] op_sel_hi:[1,0,1] neg_lo:[1,0,0] neg_hi:[1,0,0]
	v_mov_b32_e32 v12, v18
	v_mov_b32_e32 v13, v24
	v_pk_mul_f32 v[14:15], v[14:15], v[14:15]
	v_pk_fma_f32 v[152:153], v[82:83], v[6:7], v[16:17] op_sel_hi:[1,0,1] neg_lo:[1,0,0] neg_hi:[1,0,0]
	v_lshl_add_u64 v[16:17], v[138:139], 0, v[0:1]
	v_pk_fma_f32 v[138:139], v[72:73], v[6:7], v[20:21] op_sel_hi:[1,0,1] neg_lo:[1,0,0] neg_hi:[1,0,0]
	v_pk_fma_f32 v[124:125], v[12:13], v[12:13], v[14:15]
	v_pk_fma_f32 v[14:15], v[36:37], v[6:7], v[122:123] op_sel_hi:[1,0,1] neg_lo:[1,0,0] neg_hi:[1,0,0]
	v_pk_fma_f32 v[20:21], v[34:35], v[6:7], v[120:121] op_sel_hi:[1,0,1] neg_lo:[1,0,0] neg_hi:[1,0,0]
	v_mov_b32_e32 v120, v15
	v_mov_b32_e32 v121, v21
	v_mov_b32_e32 v12, v14
	v_mov_b32_e32 v13, v20
	v_pk_mul_f32 v[120:121], v[120:121], v[120:121]
	v_pk_fma_f32 v[146:147], v[84:85], v[6:7], v[30:31] op_sel_hi:[1,0,1] neg_lo:[1,0,0] neg_hi:[1,0,0]
	v_pk_fma_f32 v[156:157], v[88:89], v[6:7], v[28:29] op_sel_hi:[1,0,1] neg_lo:[1,0,0] neg_hi:[1,0,0]
	v_pk_fma_f32 v[158:159], v[92:93], v[6:7], v[98:99] op_sel_hi:[1,0,1] neg_lo:[1,0,0] neg_hi:[1,0,0]
	v_pk_fma_f32 v[162:163], v[90:91], v[6:7], v[26:27] op_sel_hi:[1,0,1] neg_lo:[1,0,0] neg_hi:[1,0,0]
	v_pk_fma_f32 v[150:151], v[96:97], v[6:7], v[32:33] op_sel_hi:[1,0,1] neg_lo:[1,0,0] neg_hi:[1,0,0]
	v_pk_fma_f32 v[164:165], v[94:95], v[6:7], v[22:23] op_sel_hi:[1,0,1] neg_lo:[1,0,0] neg_hi:[1,0,0]
	v_pk_fma_f32 v[114:115], v[76:77], v[6:7], v[114:115] op_sel_hi:[1,0,1] neg_lo:[1,0,0] neg_hi:[1,0,0]
	v_pk_fma_f32 v[140:141], v[74:75], v[6:7], v[110:111] op_sel_hi:[1,0,1] neg_lo:[1,0,0] neg_hi:[1,0,0]
	v_pk_fma_f32 v[110:111], v[80:81], v[6:7], v[112:113] op_sel_hi:[1,0,1] neg_lo:[1,0,0] neg_hi:[1,0,0]
	v_pk_fma_f32 v[106:107], v[78:79], v[6:7], v[106:107] op_sel_hi:[1,0,1] neg_lo:[1,0,0] neg_hi:[1,0,0]
	v_pk_fma_f32 v[32:33], v[52:53], v[6:7], v[108:109] op_sel_hi:[1,0,1] neg_lo:[1,0,0] neg_hi:[1,0,0]
	v_pk_fma_f32 v[98:99], v[50:51], v[6:7], v[102:103] op_sel_hi:[1,0,1] neg_lo:[1,0,0] neg_hi:[1,0,0]
	v_pk_fma_f32 v[26:27], v[56:57], v[6:7], v[104:105] op_sel_hi:[1,0,1] neg_lo:[1,0,0] neg_hi:[1,0,0]
	v_pk_fma_f32 v[30:31], v[54:55], v[6:7], v[100:101] op_sel_hi:[1,0,1] neg_lo:[1,0,0] neg_hi:[1,0,0]
	v_pk_fma_f32 v[22:23], v[60:61], v[6:7], v[130:131] op_sel_hi:[1,0,1] neg_lo:[1,0,0] neg_hi:[1,0,0]
	v_pk_fma_f32 v[28:29], v[58:59], v[6:7], v[126:127] op_sel_hi:[1,0,1] neg_lo:[1,0,0] neg_hi:[1,0,0]
	v_pk_fma_f32 v[120:121], v[12:13], v[12:13], v[120:121]
	v_pk_fma_f32 v[12:13], v[40:41], v[6:7], v[118:119] op_sel_hi:[1,0,1] neg_lo:[1,0,0] neg_hi:[1,0,0]
	v_pk_fma_f32 v[6:7], v[38:39], v[6:7], v[116:117] op_sel_hi:[1,0,1] neg_lo:[1,0,0] neg_hi:[1,0,0]
	v_mov_b32_e32 v118, v13
	v_mov_b32_e32 v119, v7
	v_pk_mul_f32 v[168:169], v[146:147], v[146:147]
	v_pk_mul_f32 v[170:171], v[152:153], v[152:153]
	v_mov_b32_e32 v116, v12
	v_mov_b32_e32 v117, v6
	v_pk_mul_f32 v[118:119], v[118:119], v[118:119]
	v_pk_mul_f32 v[174:175], v[160:161], v[160:161]
	v_pk_fma_f32 v[116:117], v[116:117], v[116:117], v[118:119]
	v_add_f32_e32 v0, v168, v169
	v_add_f32_e32 v118, v170, v171
	v_pk_mul_f32 v[172:173], v[156:157], v[156:157]
	v_add_f32_e32 v0, v118, v0
	v_add_f32_e32 v118, v174, v175
	v_pk_mul_f32 v[178:179], v[162:163], v[162:163]
	v_add_f32_e32 v0, v118, v0
	v_add_f32_e32 v118, v172, v173
	v_pk_mul_f32 v[176:177], v[158:159], v[158:159]
	v_add_f32_e32 v0, v118, v0
	v_add_f32_e32 v118, v178, v179
	v_pk_mul_f32 v[182:183], v[164:165], v[164:165]
	v_add_f32_e32 v0, v118, v0
	v_add_f32_e32 v118, v176, v177
	v_pk_mul_f32 v[180:181], v[150:151], v[150:151]
	v_add_f32_e32 v0, v118, v0
	v_add_f32_e32 v118, v182, v183
	v_pk_mul_f32 v[186:187], v[148:149], v[148:149]
	v_add_f32_e32 v0, v118, v0
	v_add_f32_e32 v118, v180, v181
	v_pk_mul_f32 v[184:185], v[144:145], v[144:145]
	v_add_f32_e32 v0, v118, v0
	v_add_f32_e32 v118, v186, v187
	v_pk_mul_f32 v[190:191], v[142:143], v[142:143]
	v_add_f32_e32 v0, v118, v0
	v_add_f32_e32 v118, v184, v185
	v_pk_mul_f32 v[188:189], v[138:139], v[138:139]
	v_add_f32_e32 v0, v118, v0
	v_add_f32_e32 v118, v190, v191
	v_pk_mul_f32 v[194:195], v[140:141], v[140:141]
	v_add_f32_e32 v0, v118, v0
	v_add_f32_e32 v118, v188, v189
	v_pk_mul_f32 v[192:193], v[114:115], v[114:115]
	v_add_f32_e32 v0, v118, v0
	v_add_f32_e32 v118, v194, v195
	v_pk_mul_f32 v[196:197], v[106:107], v[106:107]
	v_add_f32_e32 v0, v118, v0
	v_add_f32_e32 v118, v192, v193
	v_pk_mul_f32 v[112:113], v[110:111], v[110:111]
	v_add_f32_e32 v0, v118, v0
	v_add_f32_e32 v118, v196, v197
	v_pk_mul_f32 v[102:103], v[98:99], v[98:99]
	v_add_f32_e32 v0, v118, v0
	v_add_f32_e32 v112, v112, v113
	v_pk_mul_f32 v[108:109], v[32:33], v[32:33]
	v_add_f32_e32 v0, v112, v0
	v_add_f32_e32 v102, v102, v103
	v_pk_mul_f32 v[100:101], v[30:31], v[30:31]
	v_add_f32_e32 v0, v102, v0
	v_add_f32_e32 v102, v108, v109
	v_pk_mul_f32 v[104:105], v[26:27], v[26:27]
	v_add_f32_e32 v0, v102, v0
	v_add_f32_e32 v100, v100, v101
	v_pk_mul_f32 v[126:127], v[28:29], v[28:29]
	v_add_f32_e32 v0, v100, v0
	v_add_f32_e32 v100, v104, v105
	v_pk_mul_f32 v[130:131], v[22:23], v[22:23]
	v_add_f32_e32 v0, v100, v0
	v_add_f32_e32 v100, v126, v127
	v_add_f32_e32 v0, v100, v0
	v_add_f32_e32 v100, v130, v131
	v_add_f32_e32 v0, v100, v0
	v_add_f32_e32 v0, v125, v0
	v_add_f32_e32 v0, v124, v0
	v_add_f32_e32 v0, v121, v0
	v_add_f32_e32 v0, v120, v0
	v_add_f32_e32 v0, v117, v0
	v_add_f32_e32 v0, v116, v0
	v_add_f32_e32 v0, v137, v0
	v_add_f32_e32 v0, v136, v0
	v_add_f32_e32 v0, v155, v0
	v_add_f32_e32 v0, v154, v0
	ds_bpermute_b32 v100, v166, v0
	s_waitcnt lgkmcnt(0)
	v_add_f32_e32 v0, v0, v100
	v_fmamk_f32 v0, v0, 0x3c000000, v224
	v_cmp_gt_f32_e32 vcc, s59, v0
	v_mul_f32_e32 v100, 0x4b800000, v0
	s_nop 0
	v_cndmask_b32_e32 v0, v0, v100, vcc
	v_rsq_f32_e32 v0, v0
	s_nop 0
	v_mul_f32_e32 v100, 0x45800000, v0
	v_cndmask_b32_e32 v0, v0, v100, vcc
	v_sub_f32_e32 v100, 1.0, v211
	v_mul_f32_e32 v0, v100, v0
	v_pk_mul_f32 v[100:101], v[152:153], v[0:1] op_sel_hi:[1,0]
	v_pk_mul_f32 v[98:99], v[98:99], v[0:1] op_sel_hi:[1,0]
	s_waitcnt vmcnt(0)
	v_pk_mul_f32 v[2:3], v[2:3], v[100:101]
	v_pk_mul_f32 v[100:101], v[146:147], v[0:1] op_sel_hi:[1,0]
	v_cvt_pk_bf16_f32 v2, v2, v3
	v_pk_mul_f32 v[4:5], v[4:5], v[100:101]
	v_pk_mul_f32 v[100:101], v[160:161], v[0:1] op_sel_hi:[1,0]
	v_cvt_pk_bf16_f32 v3, v4, v5
	global_store_dwordx2 v[16:17], v[2:3], off
	global_load_dwordx4 v[2:5], v167, s[12:13] offset:32
	v_pk_mul_f32 v[32:33], v[32:33], v[0:1] op_sel_hi:[1,0]
	v_pk_mul_f32 v[30:31], v[30:31], v[0:1] op_sel_hi:[1,0]
	v_pk_mul_f32 v[26:27], v[26:27], v[0:1] op_sel_hi:[1,0]
	v_pk_mul_f32 v[22:23], v[22:23], v[0:1] op_sel_hi:[1,0]
	v_pk_mul_f32 v[18:19], v[18:19], v[0:1] op_sel_hi:[1,0]
	v_pk_mul_f32 v[14:15], v[14:15], v[0:1] op_sel_hi:[1,0]
	v_pk_mul_f32 v[6:7], v[6:7], v[0:1] op_sel_hi:[1,0]
	s_waitcnt vmcnt(0)
	v_pk_mul_f32 v[2:3], v[2:3], v[100:101]
	v_pk_mul_f32 v[100:101], v[156:157], v[0:1] op_sel_hi:[1,0]
	v_cvt_pk_bf16_f32 v2, v2, v3
	v_pk_mul_f32 v[4:5], v[4:5], v[100:101]
	v_pk_mul_f32 v[100:101], v[162:163], v[0:1] op_sel_hi:[1,0]
	v_cvt_pk_bf16_f32 v3, v4, v5
	global_store_dwordx2 v[16:17], v[2:3], off offset:16
	global_load_dwordx4 v[2:5], v167, s[12:13] offset:64
	s_waitcnt vmcnt(0)
	v_pk_mul_f32 v[2:3], v[2:3], v[100:101]
	v_pk_mul_f32 v[100:101], v[158:159], v[0:1] op_sel_hi:[1,0]
	v_cvt_pk_bf16_f32 v2, v2, v3
	v_pk_mul_f32 v[4:5], v[4:5], v[100:101]
	v_pk_mul_f32 v[100:101], v[164:165], v[0:1] op_sel_hi:[1,0]
	v_cvt_pk_bf16_f32 v3, v4, v5
	global_store_dwordx2 v[16:17], v[2:3], off offset:32
	global_load_dwordx4 v[2:5], v167, s[12:13] offset:96
	s_waitcnt vmcnt(0)
	v_pk_mul_f32 v[2:3], v[2:3], v[100:101]
	v_pk_mul_f32 v[100:101], v[150:151], v[0:1] op_sel_hi:[1,0]
	v_cvt_pk_bf16_f32 v2, v2, v3
	v_pk_mul_f32 v[4:5], v[4:5], v[100:101]
	v_pk_mul_f32 v[100:101], v[148:149], v[0:1] op_sel_hi:[1,0]
	v_cvt_pk_bf16_f32 v3, v4, v5
	global_store_dwordx2 v[16:17], v[2:3], off offset:48
	global_load_dwordx4 v[2:5], v167, s[12:13] offset:128
	s_waitcnt vmcnt(0)
	v_pk_mul_f32 v[2:3], v[2:3], v[100:101]
	v_pk_mul_f32 v[100:101], v[144:145], v[0:1] op_sel_hi:[1,0]
	v_cvt_pk_bf16_f32 v2, v2, v3
	v_pk_mul_f32 v[4:5], v[4:5], v[100:101]
	v_pk_mul_f32 v[100:101], v[142:143], v[0:1] op_sel_hi:[1,0]
	v_cvt_pk_bf16_f32 v3, v4, v5
	global_store_dwordx2 v[16:17], v[2:3], off offset:64
	global_load_dwordx4 v[2:5], v167, s[12:13] offset:160
	s_waitcnt vmcnt(0)
	v_pk_mul_f32 v[2:3], v[2:3], v[100:101]
	v_pk_mul_f32 v[100:101], v[138:139], v[0:1] op_sel_hi:[1,0]
	v_cvt_pk_bf16_f32 v2, v2, v3
	v_pk_mul_f32 v[4:5], v[4:5], v[100:101]
	v_pk_mul_f32 v[100:101], v[140:141], v[0:1] op_sel_hi:[1,0]
	v_cvt_pk_bf16_f32 v3, v4, v5
	global_store_dwordx2 v[16:17], v[2:3], off offset:80
	global_load_dwordx4 v[2:5], v167, s[12:13] offset:192
	s_waitcnt vmcnt(0)
	v_pk_mul_f32 v[2:3], v[2:3], v[100:101]
	v_pk_mul_f32 v[100:101], v[114:115], v[0:1] op_sel_hi:[1,0]
	v_cvt_pk_bf16_f32 v2, v2, v3
	v_pk_mul_f32 v[4:5], v[4:5], v[100:101]
	v_pk_mul_f32 v[100:101], v[106:107], v[0:1] op_sel_hi:[1,0]
	v_cvt_pk_bf16_f32 v3, v4, v5
	global_store_dwordx2 v[16:17], v[2:3], off offset:96
	global_load_dwordx4 v[2:5], v167, s[12:13] offset:224
	s_waitcnt vmcnt(0)
	v_pk_mul_f32 v[2:3], v[2:3], v[100:101]
	v_pk_mul_f32 v[100:101], v[110:111], v[0:1] op_sel_hi:[1,0]
	v_cvt_pk_bf16_f32 v2, v2, v3
	v_pk_mul_f32 v[4:5], v[4:5], v[100:101]
	s_nop 0
	v_cvt_pk_bf16_f32 v3, v4, v5
	global_store_dwordx2 v[16:17], v[2:3], off offset:112
	global_load_dwordx4 v[2:5], v167, s[12:13] offset:256
	s_waitcnt vmcnt(0)
	v_pk_mul_f32 v[2:3], v[2:3], v[98:99]
	v_pk_mul_f32 v[4:5], v[4:5], v[32:33]
	v_cvt_pk_bf16_f32 v2, v2, v3
	v_cvt_pk_bf16_f32 v3, v4, v5
	global_store_dwordx2 v[16:17], v[2:3], off offset:128
	global_load_dwordx4 v[2:5], v167, s[12:13] offset:288
	s_waitcnt vmcnt(0)
	v_pk_mul_f32 v[2:3], v[30:31], v[2:3]
	v_pk_mul_f32 v[4:5], v[26:27], v[4:5]
	v_cvt_pk_bf16_f32 v2, v2, v3
	v_cvt_pk_bf16_f32 v3, v4, v5
	global_store_dwordx2 v[16:17], v[2:3], off offset:144
	global_load_dwordx4 v[2:5], v167, s[12:13] offset:320
	v_pk_mul_f32 v[26:27], v[28:29], v[0:1] op_sel_hi:[1,0]
	s_waitcnt vmcnt(0)
	v_pk_mul_f32 v[4:5], v[22:23], v[4:5]
	v_pk_mul_f32 v[2:3], v[26:27], v[2:3]
	v_pk_mul_f32 v[22:23], v[24:25], v[0:1] op_sel_hi:[1,0]
	v_cvt_pk_bf16_f32 v2, v2, v3
	v_cvt_pk_bf16_f32 v3, v4, v5
	global_store_dwordx2 v[16:17], v[2:3], off offset:160
	global_load_dwordx4 v[2:5], v167, s[12:13] offset:352
	s_waitcnt vmcnt(0)
	v_pk_mul_f32 v[2:3], v[22:23], v[2:3]
	v_pk_mul_f32 v[4:5], v[18:19], v[4:5]
	v_cvt_pk_bf16_f32 v2, v2, v3
	v_cvt_pk_bf16_f32 v3, v4, v5
	global_store_dwordx2 v[16:17], v[2:3], off offset:176
	global_load_dwordx4 v[2:5], v167, s[12:13] offset:384
	v_pk_mul_f32 v[18:19], v[20:21], v[0:1] op_sel_hi:[1,0]
	s_waitcnt vmcnt(0)
	v_pk_mul_f32 v[4:5], v[14:15], v[4:5]
	v_pk_mul_f32 v[2:3], v[18:19], v[2:3]
	s_nop 0
	v_cvt_pk_bf16_f32 v2, v2, v3
	v_cvt_pk_bf16_f32 v3, v4, v5
	global_store_dwordx2 v[16:17], v[2:3], off offset:192
	global_load_dwordx4 v[2:5], v167, s[12:13] offset:416
	s_waitcnt vmcnt(0)
	v_pk_mul_f32 v[2:3], v[6:7], v[2:3]
	v_pk_mul_f32 v[6:7], v[12:13], v[0:1] op_sel_hi:[1,0]
	v_cvt_pk_bf16_f32 v2, v2, v3
	v_pk_mul_f32 v[4:5], v[6:7], v[4:5]
	v_mov_b32_e32 v6, v9
	v_cvt_pk_bf16_f32 v3, v4, v5
	global_store_dwordx2 v[16:17], v[2:3], off offset:208
	global_load_dwordx4 v[2:5], v167, s[12:13] offset:448
	v_mov_b32_e32 v7, v11
	v_pk_mul_f32 v[6:7], v[6:7], v[0:1] op_sel_hi:[1,0]
	v_mov_b32_e32 v9, v10
	s_waitcnt vmcnt(0)
	v_pk_mul_f32 v[2:3], v[6:7], v[2:3]
	v_pk_mul_f32 v[6:7], v[8:9], v[0:1] op_sel_hi:[1,0]
	v_cvt_pk_bf16_f32 v2, v2, v3
	v_pk_mul_f32 v[4:5], v[6:7], v[4:5]
	v_mov_b32_e32 v6, v133
	v_cvt_pk_bf16_f32 v3, v4, v5
	global_store_dwordx2 v[16:17], v[2:3], off offset:224
	global_load_dwordx4 v[2:5], v167, s[12:13] offset:480
	v_mov_b32_e32 v7, v135
	v_pk_mul_f32 v[6:7], v[6:7], v[0:1] op_sel_hi:[1,0]
	v_mov_b32_e32 v133, v134
	s_waitcnt vmcnt(0)
	v_pk_mul_f32 v[2:3], v[6:7], v[2:3]
	v_pk_mul_f32 v[6:7], v[132:133], v[0:1] op_sel_hi:[1,0]
	v_cvt_pk_bf16_f32 v2, v2, v3
	v_pk_mul_f32 v[4:5], v[6:7], v[4:5]
	s_nop 0
	v_cvt_pk_bf16_f32 v3, v4, v5
	global_store_dwordx2 v[16:17], v[2:3], off offset:240

.LBB0_623:
	v_lshl_add_u64 v[74:75], v[66:67], 0, s[26:27]
	s_add_u32 s26, s26, 0x1000
	s_addc_u32 s27, s27, 0
	s_cmpk_eq_i32 s26, 0x4000
	global_load_dword v192, v[74:75], off offset:-2048
	global_load_dword v193, v[74:75], off offset:-1536
	global_load_dword v194, v[74:75], off offset:-1024
	global_load_dword v195, v[74:75], off offset:-512
	global_load_dword v196, v[74:75], off
	global_load_dword v197, v[74:75], off offset:512
	global_load_dword v198, v[74:75], off offset:1024
	global_load_dword v199, v[74:75], off offset:1536
	s_waitcnt vmcnt(7)
	v_add_f32_e32 v68, v69, v192
	s_waitcnt vmcnt(6)
	v_add_f32_e32 v68, v68, v193
	s_waitcnt vmcnt(5)
	v_add_f32_e32 v68, v68, v194
	s_waitcnt vmcnt(4)
	v_add_f32_e32 v68, v68, v195
	s_waitcnt vmcnt(3)
	v_add_f32_e32 v68, v68, v196
	s_waitcnt vmcnt(2)
	v_add_f32_e32 v68, v68, v197
	s_waitcnt vmcnt(1)
	v_add_f32_e32 v68, v68, v198
	s_waitcnt vmcnt(0)
	v_add_f32_e32 v69, v68, v199
	s_cbranch_scc0 .LBB0_623
	v_ashrrev_i32_e32 v66, 1, v143
	v_and_b32_e32 v66, 0xffffffc0, v66
	v_add_u32_e32 v84, s29, v66
	v_lshrrev_b32_e32 v66, 3, v142
	v_add_f32_e32 v50, v50, v69
	v_and_b32_e32 v100, 4, v66
	v_lshlrev_b32_e32 v66, 1, v71
	v_mul_f32_e32 v71, 0x3d372713, v50
	v_mul_f32_e32 v71, v50, v71
	v_add_f32_e32 v51, v51, v69
	v_lshlrev_b32_e32 v124, 1, v73
	v_fma_f32 v71, v50, v71, v50
	v_mul_f32_e32 v73, 0x3d372713, v51
	v_mul_f32_e32 v71, 0x3f4c422a, v71
	v_mul_f32_e32 v73, v51, v73
	v_add_f32_e32 v71, v71, v71
	v_fma_f32 v73, v51, v73, v51
	v_mul_f32_e32 v71, 0x3fb8aa3b, v71
	v_mul_f32_e32 v73, 0x3f4c422a, v73
	v_exp_f32_e32 v71, v71
	v_add_f32_e32 v73, v73, v73
	v_add_f32_e32 v52, v52, v69
	v_mul_f32_e32 v73, 0x3fb8aa3b, v73
	v_mul_f32_e32 v75, 0x3d372713, v52
	v_exp_f32_e32 v73, v73
	v_mul_f32_e32 v75, v52, v75
	v_fma_f32 v75, v52, v75, v52
	v_add_f32_e32 v71, 1.0, v71
	v_mul_f32_e32 v75, 0x3f4c422a, v75
	v_rcp_f32_e32 v71, v71
	v_add_f32_e32 v75, v75, v75
	v_add_f32_e32 v73, 1.0, v73
	v_mul_f32_e32 v75, 0x3fb8aa3b, v75
	v_rcp_f32_e32 v73, v73
	v_exp_f32_e32 v75, v75
	v_fma_f32 v71, v71, -2.0, 1.0
	v_mul_f32_e32 v50, 0.5, v50
	v_add_f32_e32 v71, 1.0, v71
	v_add_f32_e32 v53, v53, v69
	v_mul_f32_e32 v50, v50, v71
	v_fma_f32 v71, v73, -2.0, 1.0
	v_add_f32_e32 v73, 1.0, v75
	v_mul_f32_e32 v75, 0x3d372713, v53
	v_mul_f32_e32 v75, v53, v75
	v_fma_f32 v75, v53, v75, v53
	v_mul_f32_e32 v75, 0x3f4c422a, v75
	v_add_f32_e32 v75, v75, v75
	v_mul_f32_e32 v75, 0x3fb8aa3b, v75
	v_rcp_f32_e32 v73, v73
	v_exp_f32_e32 v75, v75
	v_mul_f32_e32 v51, 0.5, v51
	v_add_f32_e32 v71, 1.0, v71
	v_mul_f32_e32 v51, v51, v71
	v_fma_f32 v71, v73, -2.0, 1.0
	v_add_f32_e32 v73, 1.0, v75
	v_rcp_f32_e32 v73, v73
	v_mul_f32_e32 v52, 0.5, v52
	v_add_f32_e32 v71, 1.0, v71
	v_mul_f32_e32 v71, v52, v71
	v_fma_f32 v52, v73, -2.0, 1.0
	v_add_f32_e32 v54, v54, v69
	v_mul_f32_e32 v73, 0x3d372713, v54
	v_mul_f32_e32 v53, 0.5, v53
	v_add_f32_e32 v52, 1.0, v52
	v_mul_f32_e32 v73, v54, v73
	v_mul_f32_e32 v75, v53, v52
	v_add_f32_e32 v53, v55, v69
	v_fma_f32 v73, v54, v73, v54
	v_mul_f32_e32 v55, 0x3d372713, v53
	v_mul_f32_e32 v73, 0x3f4c422a, v73
	v_mul_f32_e32 v55, v53, v55
	v_add_f32_e32 v73, v73, v73
	v_fma_f32 v55, v53, v55, v53
	v_mul_f32_e32 v73, 0x3fb8aa3b, v73
	v_mul_f32_e32 v55, 0x3f4c422a, v55
	v_exp_f32_e32 v73, v73
	v_add_f32_e32 v55, v55, v55
	v_mul_f32_e32 v55, 0x3fb8aa3b, v55
	v_exp_f32_e32 v55, v55
	v_add_f32_e32 v52, 1.0, v73
	v_rcp_f32_e32 v52, v52
	v_add_f32_e32 v56, v56, v69
	v_add_f32_e32 v55, 1.0, v55
	v_rcp_f32_e32 v55, v55
	v_fma_f32 v52, v52, -2.0, 1.0
	v_mul_f32_e32 v54, 0.5, v54
	v_add_f32_e32 v52, 1.0, v52
	v_mul_f32_e32 v73, 0x3d372713, v56
	v_mul_f32_e32 v73, v56, v73
	v_mul_f32_e32 v77, v54, v52
	v_fma_f32 v52, v55, -2.0, 1.0
	v_add_f32_e32 v55, v57, v69
	v_fma_f32 v73, v56, v73, v56
	v_mul_f32_e32 v57, 0x3d372713, v55
	v_mul_f32_e32 v73, 0x3f4c422a, v73
	v_mul_f32_e32 v57, v55, v57
	v_add_f32_e32 v73, v73, v73
	v_fma_f32 v57, v55, v57, v55
	v_mul_f32_e32 v73, 0x3fb8aa3b, v73
	v_mul_f32_e32 v57, 0x3f4c422a, v57
	v_exp_f32_e32 v73, v73
	v_add_f32_e32 v57, v57, v57
	v_mul_f32_e32 v57, 0x3fb8aa3b, v57
	v_exp_f32_e32 v57, v57
	v_add_f32_e32 v54, 1.0, v73
	v_mul_f32_e32 v53, 0.5, v53
	v_rcp_f32_e32 v54, v54
	v_add_f32_e32 v52, 1.0, v52
	v_mul_f32_e32 v73, v53, v52
	v_add_f32_e32 v53, 1.0, v57
	v_rcp_f32_e32 v53, v53
	v_fma_f32 v52, v54, -2.0, 1.0
	v_mul_f32_e32 v54, 0.5, v56
	v_add_f32_e32 v52, 1.0, v52
	v_mul_f32_e32 v79, v54, v52
	v_fma_f32 v52, v53, -2.0, 1.0
	v_add_f32_e32 v53, v58, v69
	v_mul_f32_e32 v54, 0x3d372713, v53
	v_mul_f32_e32 v54, v53, v54
	v_fma_f32 v54, v53, v54, v53
	v_mul_f32_e32 v54, 0x3f4c422a, v54
	v_add_f32_e32 v54, v54, v54
	v_mul_f32_e32 v54, 0x3fb8aa3b, v54
	v_exp_f32_e32 v54, v54
	v_mul_f32_e32 v55, 0.5, v55
	v_add_f32_e32 v52, 1.0, v52
	v_mul_f32_e32 v81, v55, v52
	v_add_f32_e32 v52, 1.0, v54
	v_add_f32_e32 v54, v59, v69
	v_mul_f32_e32 v55, 0x3d372713, v54
	v_mul_f32_e32 v55, v54, v55
	v_fma_f32 v55, v54, v55, v54
	v_mul_f32_e32 v55, 0x3f4c422a, v55
	v_add_f32_e32 v55, v55, v55
	v_mul_f32_e32 v55, 0x3fb8aa3b, v55
	v_add_f32_e32 v56, v60, v69
	v_exp_f32_e32 v55, v55
	v_mul_f32_e32 v57, 0x3d372713, v56
	v_mul_f32_e32 v57, v56, v57
	v_fma_f32 v57, v56, v57, v56
	v_rcp_f32_e32 v52, v52
	v_mul_f32_e32 v57, 0x3f4c422a, v57
	v_add_f32_e32 v55, 1.0, v55
	v_add_f32_e32 v57, v57, v57
	v_rcp_f32_e32 v55, v55
	v_mul_f32_e32 v57, 0x3fb8aa3b, v57
	v_exp_f32_e32 v57, v57
	v_fma_f32 v52, v52, -2.0, 1.0
	v_mul_f32_e32 v53, 0.5, v53
	v_add_f32_e32 v52, 1.0, v52
	v_mul_f32_e32 v83, v53, v52
	v_fma_f32 v52, v55, -2.0, 1.0
	v_add_f32_e32 v55, v61, v69
	v_mul_f32_e32 v53, 0.5, v54
	v_add_f32_e32 v54, 1.0, v57
	v_mul_f32_e32 v57, 0x3d372713, v55
	v_mul_f32_e32 v57, v55, v57
	v_fma_f32 v57, v55, v57, v55
	v_mul_f32_e32 v57, 0x3f4c422a, v57
	v_add_f32_e32 v57, v57, v57
	v_mul_f32_e32 v57, 0x3fb8aa3b, v57
	v_exp_f32_e32 v57, v57
	v_rcp_f32_e32 v54, v54
	v_add_f32_e32 v52, 1.0, v52
	v_mul_f32_e32 v85, v53, v52
	v_add_f32_e32 v53, 1.0, v57
	v_rcp_f32_e32 v53, v53
	v_fma_f32 v52, v54, -2.0, 1.0
	v_mul_f32_e32 v54, 0.5, v56
	v_add_f32_e32 v52, 1.0, v52
	v_mul_f32_e32 v87, v54, v52
	v_fma_f32 v52, v53, -2.0, 1.0
	v_add_f32_e32 v53, v62, v69
	v_mul_f32_e32 v54, 0x3d372713, v53
	v_mul_f32_e32 v54, v53, v54
	v_fma_f32 v54, v53, v54, v53
	v_mul_f32_e32 v54, 0x3f4c422a, v54
	v_add_f32_e32 v54, v54, v54
	v_mul_f32_e32 v54, 0x3fb8aa3b, v54
	v_exp_f32_e32 v54, v54
	v_mul_f32_e32 v55, 0.5, v55
	v_add_f32_e32 v52, 1.0, v52
	v_mul_f32_e32 v89, v55, v52
	v_add_f32_e32 v52, 1.0, v54
	v_add_f32_e32 v54, v63, v69
	v_mul_f32_e32 v55, 0x3d372713, v54
	v_mul_f32_e32 v55, v54, v55
	v_fma_f32 v55, v54, v55, v54
	v_mul_f32_e32 v55, 0x3f4c422a, v55
	v_add_f32_e32 v55, v55, v55
	v_mul_f32_e32 v55, 0x3fb8aa3b, v55
	v_add_f32_e32 v56, v64, v69
	v_exp_f32_e32 v55, v55
	v_mul_f32_e32 v57, 0x3d372713, v56
	v_mul_f32_e32 v57, v56, v57
	v_fma_f32 v57, v56, v57, v56
	v_rcp_f32_e32 v52, v52
	v_mul_f32_e32 v57, 0x3f4c422a, v57
	v_add_f32_e32 v55, 1.0, v55
	v_add_f32_e32 v57, v57, v57
	v_rcp_f32_e32 v55, v55
	v_mul_f32_e32 v57, 0x3fb8aa3b, v57
	v_exp_f32_e32 v57, v57
	v_fma_f32 v52, v52, -2.0, 1.0
	v_mul_f32_e32 v53, 0.5, v53
	v_add_f32_e32 v52, 1.0, v52
	v_mul_f32_e32 v91, v53, v52
	v_fma_f32 v52, v55, -2.0, 1.0
	v_add_f32_e32 v55, v65, v69
	v_mul_f32_e32 v53, 0.5, v54
	v_add_f32_e32 v54, 1.0, v57
	v_mul_f32_e32 v57, 0x3d372713, v55
	v_mul_f32_e32 v57, v55, v57
	v_fma_f32 v57, v55, v57, v55
	v_mul_f32_e32 v57, 0x3f4c422a, v57
	v_add_f32_e32 v57, v57, v57
	v_mul_f32_e32 v57, 0x3fb8aa3b, v57
	v_exp_f32_e32 v57, v57
	s_lshl_b32 s0, s0, 3
	v_rcp_f32_e32 v54, v54
	v_add_f32_e32 v52, 1.0, v52
	s_or_b32 s0, s0, s28
	v_mul_f32_e32 v69, v53, v52
	v_add_f32_e32 v53, 1.0, v57
	s_ashr_i32 s1, s0, 31
	v_rcp_f32_e32 v53, v53
	s_lshl_b64 s[0:1], s[0:1], 17
	v_bfe_u32 v67, v142, 3, 3
	s_add_u32 s0, s49, s0
	v_fma_f32 v52, v54, -2.0, 1.0
	v_or_b32_e32 v80, 3, v67
	v_or_b32_e32 v76, 11, v67
	v_or_b32_e32 v72, 19, v67
	v_or_b32_e32 v68, 27, v67
	s_addc_u32 s1, s50, s1
	v_mov_b32_e32 v67, v1
	v_mul_f32_e32 v54, 0.5, v56
	v_add_f32_e32 v52, 1.0, v52
	v_or_b32_e32 v82, 1, v100
	v_ashrrev_i32_e32 v103, 31, v84
	v_or_b32_e32 v102, v84, v100
	v_lshl_add_u64 v[66:67], s[0:1], 0, v[66:67]
	v_mov_b32_e32 v125, v1
	v_mul_f32_e32 v93, v54, v52
	v_fma_f32 v52, v53, -2.0, 1.0
	v_or_b32_e32 v98, 2, v100
	v_or_b32_e32 v118, v84, v82
	v_mov_b32_e32 v119, v103
	v_lshl_add_u64 v[66:67], v[66:67], 0, v[124:125]
	v_lshlrev_b64 v[132:133], 8, v[102:103]
	v_mul_f32_e32 v53, 0.5, v55
	v_add_f32_e32 v52, 1.0, v52
	v_or_b32_e32 v104, v84, v98
	v_mov_b32_e32 v105, v103
	v_lshlrev_b64 v[130:131], 8, v[118:119]
	v_mul_f32_e32 v95, v53, v52
	v_cvt_pk_bf16_f32 v50, v50, s0
	v_lshl_add_u64 v[52:53], v[66:67], 0, v[132:133]
	v_or_b32_e32 v96, 8, v100
	v_or_b32_e32 v120, v84, v80
	v_mov_b32_e32 v121, v103
	v_lshlrev_b64 v[128:129], 8, v[104:105]
	global_store_short v[52:53], v50, off
	v_cvt_pk_bf16_f32 v50, v51, s0
	v_lshl_add_u64 v[54:55], v[66:67], 0, v[130:131]
	v_or_b32_e32 v78, 9, v100
	v_or_b32_e32 v106, v84, v96
	v_mov_b32_e32 v107, v103
	v_lshlrev_b64 v[126:127], 8, v[120:121]
	global_store_short v[54:55], v50, off
	v_cvt_pk_bf16_f32 v50, v71, s0
	v_lshl_add_u64 v[56:57], v[66:67], 0, v[128:129]
	v_or_b32_e32 v94, 10, v100
	v_or_b32_e32 v122, v84, v78
	v_mov_b32_e32 v123, v103
	v_lshlrev_b64 v[124:125], 8, v[106:107]
	global_store_short v[56:57], v50, off
	v_cvt_pk_bf16_f32 v50, v75, s0
	v_lshl_add_u64 v[58:59], v[66:67], 0, v[126:127]
	v_or_b32_e32 v108, v84, v94
	v_mov_b32_e32 v109, v103
	v_lshlrev_b64 v[122:123], 8, v[122:123]
	global_store_short v[58:59], v50, off
	v_cvt_pk_bf16_f32 v50, v77, s0
	v_lshl_add_u64 v[60:61], v[66:67], 0, v[124:125]
	v_or_b32_e32 v92, 16, v100
	v_or_b32_e32 v134, v84, v76
	v_mov_b32_e32 v135, v103
	v_lshlrev_b64 v[120:121], 8, v[108:109]
	global_store_short v[60:61], v50, off
	v_cvt_pk_bf16_f32 v50, v73, s0
	v_lshl_add_u64 v[62:63], v[66:67], 0, v[122:123]
	v_or_b32_e32 v74, 17, v100
	v_or_b32_e32 v110, v84, v92
	v_mov_b32_e32 v111, v103
	v_mov_b32_e32 v113, v103
	v_mov_b32_e32 v115, v103
	v_mov_b32_e32 v117, v103
	v_mov_b32_e32 v137, v103
	v_mov_b32_e32 v139, v103
	v_mov_b32_e32 v141, v103
	v_mov_b32_e32 v143, v103
	v_lshlrev_b64 v[102:103], 8, v[134:135]
	global_store_short v[62:63], v50, off
	v_cvt_pk_bf16_f32 v50, v79, s0
	v_lshl_add_u64 v[64:65], v[66:67], 0, v[120:121]
	v_or_b32_e32 v90, 18, v100
	v_or_b32_e32 v136, v84, v74
	v_lshlrev_b64 v[104:105], 8, v[110:111]
	global_store_short v[64:65], v50, off
	v_cvt_pk_bf16_f32 v50, v81, s0
	v_lshl_add_u64 v[102:103], v[66:67], 0, v[102:103]
	v_or_b32_e32 v112, v84, v90
	v_lshlrev_b64 v[106:107], 8, v[136:137]
	global_store_short v[102:103], v50, off
	v_cvt_pk_bf16_f32 v50, v83, s0
	v_lshl_add_u64 v[104:105], v[66:67], 0, v[104:105]
	v_or_b32_e32 v88, 24, v100
	v_or_b32_e32 v138, v84, v72
	v_lshlrev_b64 v[108:109], 8, v[112:113]
	global_store_short v[104:105], v50, off
	v_cvt_pk_bf16_f32 v50, v85, s0
	v_lshl_add_u64 v[106:107], v[66:67], 0, v[106:107]
	v_or_b32_e32 v70, 25, v100
	v_or_b32_e32 v114, v84, v88
	v_lshlrev_b64 v[110:111], 8, v[138:139]
	global_store_short v[106:107], v50, off
	v_cvt_pk_bf16_f32 v50, v87, s0
	v_lshl_add_u64 v[108:109], v[66:67], 0, v[108:109]
	v_or_b32_e32 v86, 26, v100
	v_or_b32_e32 v140, v84, v70
	v_lshlrev_b64 v[112:113], 8, v[114:115]
	global_store_short v[108:109], v50, off
	v_cvt_pk_bf16_f32 v50, v89, s0
	v_lshl_add_u64 v[110:111], v[66:67], 0, v[110:111]
	v_or_b32_e32 v116, v84, v86
	v_lshlrev_b64 v[114:115], 8, v[140:141]
	global_store_short v[110:111], v50, off
	v_cvt_pk_bf16_f32 v50, v91, s0
	v_lshl_add_u64 v[112:113], v[66:67], 0, v[112:113]
	v_or_b32_e32 v142, v84, v68
	v_lshlrev_b64 v[116:117], 8, v[116:117]
	global_store_short v[112:113], v50, off
	v_cvt_pk_bf16_f32 v50, v69, s0
	v_lshl_add_u64 v[114:115], v[66:67], 0, v[114:115]
	v_lshlrev_b64 v[118:119], 8, v[142:143]
	global_store_short v[114:115], v50, off
	v_cvt_pk_bf16_f32 v50, v93, s0
	v_lshl_add_u64 v[116:117], v[66:67], 0, v[116:117]
	global_store_short v[116:117], v50, off
	v_cvt_pk_bf16_f32 v50, v95, s0
	v_lshl_add_u64 v[118:119], v[66:67], 0, v[118:119]
	v_lshl_add_u64 v[120:121], s[4:5], 0, v[0:1]
	global_store_short v[118:119], v50, off
	v_lshl_add_u64 v[50:51], s[24:25], 0, v[120:121]
	v_mov_b32_e32 v0, 0
	s_mov_b64 s[0:1], 0
.LBB0_625:
	v_lshl_add_u64 v[122:123], v[50:51], 0, s[0:1]
	s_add_u32 s0, s0, 0x1000
	s_addc_u32 s1, s1, 0
	s_cmpk_lg_i32 s0, 0x4000
	global_load_dword v192, v[122:123], off offset:-2048
	global_load_dword v193, v[122:123], off offset:-1536
	global_load_dword v194, v[122:123], off offset:-1024
	global_load_dword v195, v[122:123], off offset:-512
	global_load_dword v196, v[122:123], off
	global_load_dword v197, v[122:123], off offset:512
	global_load_dword v198, v[122:123], off offset:1024
	global_load_dword v199, v[122:123], off offset:1536
	s_waitcnt vmcnt(7)
	v_add_f32_e32 v0, v0, v192
	s_waitcnt vmcnt(6)
	v_add_f32_e32 v0, v0, v193
	s_waitcnt vmcnt(5)
	v_add_f32_e32 v0, v0, v194
	s_waitcnt vmcnt(4)
	v_add_f32_e32 v0, v0, v195
	s_waitcnt vmcnt(3)
	v_add_f32_e32 v0, v0, v196
	s_waitcnt vmcnt(2)
	v_add_f32_e32 v0, v0, v197
	s_waitcnt vmcnt(1)
	v_add_f32_e32 v0, v0, v198
	s_waitcnt vmcnt(0)
	v_add_f32_e32 v0, v0, v199
	s_cbranch_scc1 .LBB0_625
	v_add_f32_e32 v34, v34, v0
	v_mul_f32_e32 v69, 0x3d372713, v34
	v_mul_f32_e32 v69, v34, v69
	v_fma_f32 v69, v34, v69, v34
	v_mul_f32_e32 v69, 0x3f4c422a, v69
	v_add_f32_e32 v69, v69, v69
	v_mul_f32_e32 v69, 0x3fb8aa3b, v69
	v_exp_f32_e32 v69, v69
	v_mul_f32_e32 v34, 0.5, v34
	v_add_f32_e32 v35, v35, v0
	v_add_f32_e32 v36, v36, v0
	v_add_f32_e32 v69, 1.0, v69
	v_rcp_f32_e32 v69, v69
	v_add_f32_e32 v37, v37, v0
	v_add_f32_e32 v38, v38, v0
	v_add_f32_e32 v39, v39, v0
	v_fma_f32 v69, v69, -2.0, 1.0
	v_add_f32_e32 v69, 1.0, v69
	v_mul_f32_e32 v34, v34, v69
	v_mul_f32_e32 v69, 0x3d372713, v35
	v_mul_f32_e32 v69, v35, v69
	v_fma_f32 v69, v35, v69, v35
	v_mul_f32_e32 v69, 0x3f4c422a, v69
	v_add_f32_e32 v69, v69, v69
	v_mul_f32_e32 v69, 0x3fb8aa3b, v69
	v_exp_f32_e32 v69, v69
	v_mul_f32_e32 v35, 0.5, v35
	v_add_f32_e32 v40, v40, v0
	v_add_f32_e32 v41, v41, v0
	v_add_f32_e32 v69, 1.0, v69
	v_rcp_f32_e32 v69, v69
	v_add_f32_e32 v42, v42, v0
	v_add_f32_e32 v43, v43, v0
	v_add_f32_e32 v44, v44, v0
	v_fma_f32 v69, v69, -2.0, 1.0
	v_add_f32_e32 v69, 1.0, v69
	v_mul_f32_e32 v35, v35, v69
	v_mul_f32_e32 v69, 0x3d372713, v36
	v_mul_f32_e32 v69, v36, v69
	v_fma_f32 v69, v36, v69, v36
	v_mul_f32_e32 v69, 0x3f4c422a, v69
	v_add_f32_e32 v69, v69, v69
	v_mul_f32_e32 v69, 0x3fb8aa3b, v69
	v_exp_f32_e32 v69, v69
	v_mul_f32_e32 v36, 0.5, v36
	v_add_f32_e32 v45, v45, v0
	v_add_f32_e32 v46, v46, v0
	v_add_f32_e32 v69, 1.0, v69
	v_rcp_f32_e32 v69, v69
	v_add_f32_e32 v47, v47, v0
	v_add_f32_e32 v48, v48, v0
	v_add_f32_e32 v0, v49, v0
	v_fma_f32 v69, v69, -2.0, 1.0
	v_add_f32_e32 v69, 1.0, v69
	v_mul_f32_e32 v36, v36, v69
	v_mul_f32_e32 v69, 0x3d372713, v37
	v_mul_f32_e32 v69, v37, v69
	v_fma_f32 v69, v37, v69, v37
	v_mul_f32_e32 v69, 0x3f4c422a, v69
	v_add_f32_e32 v69, v69, v69
	v_mul_f32_e32 v69, 0x3fb8aa3b, v69
	v_exp_f32_e32 v69, v69
	v_mul_f32_e32 v37, 0.5, v37
	v_mul_f32_e32 v49, 0x3d372713, v0
	v_mul_f32_e32 v49, v0, v49
	v_add_f32_e32 v69, 1.0, v69
	v_rcp_f32_e32 v69, v69
	v_fma_f32 v49, v0, v49, v0
	v_mul_f32_e32 v49, 0x3f4c422a, v49
	v_add_f32_e32 v49, v49, v49
	v_fma_f32 v69, v69, -2.0, 1.0
	v_add_f32_e32 v69, 1.0, v69
	v_mul_f32_e32 v37, v37, v69
	v_mul_f32_e32 v69, 0x3d372713, v38
	v_mul_f32_e32 v69, v38, v69
	v_fma_f32 v69, v38, v69, v38
	v_mul_f32_e32 v69, 0x3f4c422a, v69
	v_add_f32_e32 v69, v69, v69
	v_mul_f32_e32 v69, 0x3fb8aa3b, v69
	v_exp_f32_e32 v69, v69
	v_mul_f32_e32 v38, 0.5, v38
	v_cvt_pk_bf16_f32 v34, v34, s0
	v_mul_f32_e32 v49, 0x3fb8aa3b, v49
	v_add_f32_e32 v69, 1.0, v69
	v_rcp_f32_e32 v69, v69
	global_store_short v[52:53], v34, off offset:64
	v_cvt_pk_bf16_f32 v34, v35, s0
	v_exp_f32_e32 v49, v49
	v_fma_f32 v69, v69, -2.0, 1.0
	v_add_f32_e32 v69, 1.0, v69
	v_mul_f32_e32 v38, v38, v69
	v_mul_f32_e32 v69, 0x3d372713, v39
	v_mul_f32_e32 v69, v39, v69
	v_fma_f32 v69, v39, v69, v39
	v_mul_f32_e32 v69, 0x3f4c422a, v69
	v_add_f32_e32 v69, v69, v69
	v_mul_f32_e32 v69, 0x3fb8aa3b, v69
	v_exp_f32_e32 v69, v69
	v_mul_f32_e32 v39, 0.5, v39
	global_store_short v[54:55], v34, off offset:64
	v_cvt_pk_bf16_f32 v34, v36, s0
	v_add_f32_e32 v69, 1.0, v69
	v_rcp_f32_e32 v69, v69
	global_store_short v[56:57], v34, off offset:64
	v_cvt_pk_bf16_f32 v34, v37, s0
	global_store_short v[58:59], v34, off offset:64
	v_fma_f32 v69, v69, -2.0, 1.0
	v_add_f32_e32 v69, 1.0, v69
	v_mul_f32_e32 v39, v39, v69
	v_mul_f32_e32 v69, 0x3d372713, v40
	v_mul_f32_e32 v69, v40, v69
	v_fma_f32 v69, v40, v69, v40
	v_mul_f32_e32 v69, 0x3f4c422a, v69
	v_add_f32_e32 v69, v69, v69
	v_mul_f32_e32 v69, 0x3fb8aa3b, v69
	v_exp_f32_e32 v69, v69
	v_mul_f32_e32 v40, 0.5, v40
	v_cvt_pk_bf16_f32 v34, v38, s0
	global_store_short v[60:61], v34, off offset:64
	v_add_f32_e32 v69, 1.0, v69
	v_rcp_f32_e32 v69, v69
	v_cvt_pk_bf16_f32 v34, v39, s0
	v_add_f32_e32 v49, 1.0, v49
	global_store_short v[62:63], v34, off offset:64
	v_fma_f32 v69, v69, -2.0, 1.0
	v_add_f32_e32 v69, 1.0, v69
	v_mul_f32_e32 v40, v40, v69
	v_mul_f32_e32 v69, 0x3d372713, v41
	v_mul_f32_e32 v69, v41, v69
	v_fma_f32 v69, v41, v69, v41
	v_mul_f32_e32 v69, 0x3f4c422a, v69
	v_add_f32_e32 v69, v69, v69
	v_mul_f32_e32 v69, 0x3fb8aa3b, v69
	v_exp_f32_e32 v69, v69
	v_mul_f32_e32 v41, 0.5, v41
	v_cvt_pk_bf16_f32 v34, v40, s0
	v_rcp_f32_e32 v49, v49
	v_add_f32_e32 v69, 1.0, v69
	v_rcp_f32_e32 v69, v69
	global_store_short v[64:65], v34, off offset:64
	v_fma_f32 v49, v49, -2.0, 1.0
	v_mul_f32_e32 v0, 0.5, v0
	v_fma_f32 v69, v69, -2.0, 1.0
	v_add_f32_e32 v69, 1.0, v69
	v_mul_f32_e32 v41, v41, v69
	v_mul_f32_e32 v69, 0x3d372713, v42
	v_mul_f32_e32 v69, v42, v69
	v_fma_f32 v69, v42, v69, v42
	v_mul_f32_e32 v69, 0x3f4c422a, v69
	v_add_f32_e32 v69, v69, v69
	v_mul_f32_e32 v69, 0x3fb8aa3b, v69
	v_exp_f32_e32 v69, v69
	v_mul_f32_e32 v42, 0.5, v42
	v_cvt_pk_bf16_f32 v34, v41, s0
	global_store_short v[102:103], v34, off offset:64
	v_add_f32_e32 v69, 1.0, v69
	v_rcp_f32_e32 v69, v69
	v_add_f32_e32 v49, 1.0, v49
	v_mul_f32_e32 v0, v0, v49
	v_cvt_pk_bf16_f32 v0, v0, s0
	v_fma_f32 v69, v69, -2.0, 1.0
	v_add_f32_e32 v69, 1.0, v69
	v_mul_f32_e32 v42, v42, v69
	v_mul_f32_e32 v69, 0x3d372713, v43
	v_mul_f32_e32 v69, v43, v69
	v_fma_f32 v69, v43, v69, v43
	v_mul_f32_e32 v69, 0x3f4c422a, v69
	v_add_f32_e32 v69, v69, v69
	v_mul_f32_e32 v69, 0x3fb8aa3b, v69
	v_exp_f32_e32 v69, v69
	v_mul_f32_e32 v43, 0.5, v43
	v_cvt_pk_bf16_f32 v34, v42, s0
	global_store_short v[104:105], v34, off offset:64
	v_add_f32_e32 v69, 1.0, v69
	v_rcp_f32_e32 v69, v69
	global_store_short v[118:119], v0, off offset:64
	v_mov_b32_e32 v0, 0
	v_fma_f32 v69, v69, -2.0, 1.0
	v_add_f32_e32 v69, 1.0, v69
	v_mul_f32_e32 v43, v43, v69
	v_mul_f32_e32 v69, 0x3d372713, v44
	v_mul_f32_e32 v69, v44, v69
	v_fma_f32 v69, v44, v69, v44
	v_mul_f32_e32 v69, 0x3f4c422a, v69
	v_add_f32_e32 v69, v69, v69
	v_mul_f32_e32 v69, 0x3fb8aa3b, v69
	v_exp_f32_e32 v69, v69
	v_mul_f32_e32 v44, 0.5, v44
	v_cvt_pk_bf16_f32 v34, v43, s0
	global_store_short v[106:107], v34, off offset:64
	v_add_f32_e32 v69, 1.0, v69
	v_rcp_f32_e32 v69, v69
	s_nop 0
	v_fma_f32 v69, v69, -2.0, 1.0
	v_add_f32_e32 v69, 1.0, v69
	v_mul_f32_e32 v44, v44, v69
	v_mul_f32_e32 v69, 0x3d372713, v45
	v_mul_f32_e32 v69, v45, v69
	v_fma_f32 v69, v45, v69, v45
	v_mul_f32_e32 v69, 0x3f4c422a, v69
	v_add_f32_e32 v69, v69, v69
	v_mul_f32_e32 v69, 0x3fb8aa3b, v69
	v_exp_f32_e32 v69, v69
	v_mul_f32_e32 v45, 0.5, v45
	v_cvt_pk_bf16_f32 v34, v44, s0
	global_store_short v[108:109], v34, off offset:64
	v_add_f32_e32 v69, 1.0, v69
	v_rcp_f32_e32 v69, v69
	s_nop 0
	v_fma_f32 v69, v69, -2.0, 1.0
	v_add_f32_e32 v69, 1.0, v69
	v_mul_f32_e32 v45, v45, v69
	v_mul_f32_e32 v69, 0x3d372713, v46
	v_mul_f32_e32 v69, v46, v69
	v_fma_f32 v69, v46, v69, v46
	v_mul_f32_e32 v69, 0x3f4c422a, v69
	v_add_f32_e32 v69, v69, v69
	v_mul_f32_e32 v69, 0x3fb8aa3b, v69
	v_exp_f32_e32 v69, v69
	v_mul_f32_e32 v46, 0.5, v46
	v_cvt_pk_bf16_f32 v34, v45, s0
	global_store_short v[110:111], v34, off offset:64
	v_add_f32_e32 v69, 1.0, v69
	v_rcp_f32_e32 v69, v69
	s_nop 0
	v_fma_f32 v69, v69, -2.0, 1.0
	v_add_f32_e32 v69, 1.0, v69
	v_mul_f32_e32 v46, v46, v69
	v_mul_f32_e32 v69, 0x3d372713, v47
	v_mul_f32_e32 v69, v47, v69
	v_fma_f32 v69, v47, v69, v47
	v_mul_f32_e32 v69, 0x3f4c422a, v69
	v_add_f32_e32 v69, v69, v69
	v_mul_f32_e32 v69, 0x3fb8aa3b, v69
	v_exp_f32_e32 v69, v69
	v_mul_f32_e32 v47, 0.5, v47
	v_cvt_pk_bf16_f32 v34, v46, s0
	global_store_short v[112:113], v34, off offset:64
	v_add_f32_e32 v69, 1.0, v69
	v_rcp_f32_e32 v69, v69
	s_nop 0
	v_fma_f32 v69, v69, -2.0, 1.0
	v_add_f32_e32 v69, 1.0, v69
	v_mul_f32_e32 v47, v47, v69
	v_mul_f32_e32 v69, 0x3d372713, v48
	v_mul_f32_e32 v69, v48, v69
	v_fma_f32 v69, v48, v69, v48
	v_mul_f32_e32 v69, 0x3f4c422a, v69
	v_add_f32_e32 v69, v69, v69
	v_mul_f32_e32 v69, 0x3fb8aa3b, v69
	v_exp_f32_e32 v69, v69
	v_mul_f32_e32 v48, 0.5, v48
	v_cvt_pk_bf16_f32 v34, v47, s0
	global_store_short v[114:115], v34, off offset:64
	v_add_f32_e32 v69, 1.0, v69
	v_rcp_f32_e32 v69, v69
	s_nop 0
	v_fma_f32 v69, v69, -2.0, 1.0
	v_add_f32_e32 v69, 1.0, v69
	v_mul_f32_e32 v48, v48, v69
	v_cvt_pk_bf16_f32 v34, v48, s0
	global_store_short v[116:117], v34, off offset:64
	v_lshl_add_u64 v[34:35], s[22:23], 0, v[120:121]
	s_mov_b64 s[0:1], 0
.LBB0_627:
	v_lshl_add_u64 v[36:37], v[34:35], 0, s[0:1]
	s_add_u32 s0, s0, 0x1000
	s_addc_u32 s1, s1, 0
	s_cmpk_lg_i32 s0, 0x4000
	global_load_dword v192, v[36:37], off offset:-2048
	global_load_dword v193, v[36:37], off offset:-1536
	global_load_dword v194, v[36:37], off offset:-1024
	global_load_dword v195, v[36:37], off offset:-512
	global_load_dword v196, v[36:37], off
	global_load_dword v197, v[36:37], off offset:512
	global_load_dword v198, v[36:37], off offset:1024
	global_load_dword v199, v[36:37], off offset:1536
	s_waitcnt vmcnt(7)
	v_add_f32_e32 v0, v0, v192
	s_waitcnt vmcnt(6)
	v_add_f32_e32 v0, v0, v193
	s_waitcnt vmcnt(5)
	v_add_f32_e32 v0, v0, v194
	s_waitcnt vmcnt(4)
	v_add_f32_e32 v0, v0, v195
	s_waitcnt vmcnt(3)
	v_add_f32_e32 v0, v0, v196
	s_waitcnt vmcnt(2)
	v_add_f32_e32 v0, v0, v197
	s_waitcnt vmcnt(1)
	v_add_f32_e32 v0, v0, v198
	s_waitcnt vmcnt(0)
	v_add_f32_e32 v0, v0, v199
	s_cbranch_scc1 .LBB0_627
	v_or_b32_e32 v58, 32, v84
	v_ashrrev_i32_e32 v35, 31, v58
	v_or_b32_e32 v38, v58, v96
	v_mov_b32_e32 v39, v35
	v_or_b32_e32 v44, v58, v90
	v_mov_b32_e32 v45, v35
	v_or_b32_e32 v70, v58, v70
	v_mov_b32_e32 v71, v35
	v_add_f32_e32 v18, v18, v0
	v_or_b32_e32 v34, v58, v100
	v_or_b32_e32 v36, v58, v98
	v_or_b32_e32 v40, v58, v94
	v_or_b32_e32 v42, v58, v92
	v_or_b32_e32 v46, v58, v88
	v_or_b32_e32 v48, v58, v86
	v_or_b32_e32 v52, v58, v82
	v_or_b32_e32 v54, v58, v80
	v_or_b32_e32 v56, v58, v78
	v_or_b32_e32 v76, v58, v76
	v_or_b32_e32 v74, v58, v74
	v_or_b32_e32 v72, v58, v72
	v_or_b32_e32 v78, v58, v68
	v_lshlrev_b64 v[58:59], 8, v[38:39]
	v_lshlrev_b64 v[38:39], 8, v[44:45]
	v_lshlrev_b64 v[44:45], 8, v[70:71]
	v_mul_f32_e32 v70, 0x3d372713, v18
	v_mul_f32_e32 v70, v18, v70
	v_fma_f32 v70, v18, v70, v18
	v_mul_f32_e32 v70, 0x3f4c422a, v70
	v_add_f32_e32 v70, v70, v70
	v_mul_f32_e32 v70, 0x3fb8aa3b, v70
	v_exp_f32_e32 v70, v70
	v_mul_f32_e32 v18, 0.5, v18
	v_add_f32_e32 v19, v19, v0
	v_mov_b32_e32 v41, v35
	v_add_f32_e32 v70, 1.0, v70
	v_rcp_f32_e32 v70, v70
	v_mov_b32_e32 v55, v35
	v_mov_b32_e32 v73, v35
	v_lshlrev_b64 v[60:61], 8, v[54:55]
	v_fma_f32 v70, v70, -2.0, 1.0
	v_add_f32_e32 v70, 1.0, v70
	v_mul_f32_e32 v18, v18, v70
	v_mul_f32_e32 v70, 0x3d372713, v19
	v_mul_f32_e32 v70, v19, v70
	v_fma_f32 v70, v19, v70, v19
	v_mul_f32_e32 v70, 0x3f4c422a, v70
	v_add_f32_e32 v70, v70, v70
	v_mul_f32_e32 v70, 0x3fb8aa3b, v70
	v_exp_f32_e32 v70, v70
	v_mul_f32_e32 v19, 0.5, v19
	v_lshlrev_b64 v[54:55], 8, v[40:41]
	v_lshlrev_b64 v[40:41], 8, v[72:73]
	v_add_f32_e32 v70, 1.0, v70
	v_rcp_f32_e32 v70, v70
	v_mov_b32_e32 v37, v35
	v_mov_b32_e32 v75, v35
	v_lshlrev_b64 v[62:63], 8, v[36:37]
	v_fma_f32 v70, v70, -2.0, 1.0
	v_add_f32_e32 v70, 1.0, v70
	v_mul_f32_e32 v70, v19, v70
	v_add_f32_e32 v19, v20, v0
	v_mul_f32_e32 v20, 0x3d372713, v19
	v_mul_f32_e32 v20, v19, v20
	v_fma_f32 v20, v19, v20, v19
	v_mul_f32_e32 v20, 0x3f4c422a, v20
	v_add_f32_e32 v20, v20, v20
	v_mul_f32_e32 v20, 0x3fb8aa3b, v20
	v_exp_f32_e32 v20, v20
	v_mul_f32_e32 v19, 0.5, v19
	v_lshlrev_b64 v[36:37], 8, v[74:75]
	v_mov_b32_e32 v53, v35
	v_add_f32_e32 v20, 1.0, v20
	v_rcp_f32_e32 v20, v20
	v_mov_b32_e32 v77, v35
	v_lshlrev_b64 v[64:65], 8, v[52:53]
	v_lshlrev_b64 v[52:53], 8, v[76:77]
	v_fma_f32 v20, v20, -2.0, 1.0
	v_add_f32_e32 v20, 1.0, v20
	v_mul_f32_e32 v71, v19, v20
	v_add_f32_e32 v19, v21, v0
	v_mul_f32_e32 v20, 0x3d372713, v19
	v_mul_f32_e32 v20, v19, v20
	v_fma_f32 v20, v19, v20, v19
	v_mul_f32_e32 v20, 0x3f4c422a, v20
	v_add_f32_e32 v20, v20, v20
	v_mul_f32_e32 v20, 0x3fb8aa3b, v20
	v_exp_f32_e32 v20, v20
	v_mul_f32_e32 v19, 0.5, v19
	v_mov_b32_e32 v43, v35
	v_mov_b32_e32 v47, v35
	v_add_f32_e32 v20, 1.0, v20
	v_rcp_f32_e32 v20, v20
	v_mov_b32_e32 v49, v35
	v_mov_b32_e32 v79, v35
	v_mov_b32_e32 v57, v35
	v_fma_f32 v20, v20, -2.0, 1.0
	v_add_f32_e32 v20, 1.0, v20
	v_mul_f32_e32 v72, v19, v20
	v_add_f32_e32 v19, v22, v0
	v_mul_f32_e32 v20, 0x3d372713, v19
	v_mul_f32_e32 v20, v19, v20
	v_fma_f32 v20, v19, v20, v19
	v_mul_f32_e32 v20, 0x3f4c422a, v20
	v_add_f32_e32 v20, v20, v20
	v_mul_f32_e32 v20, 0x3fb8aa3b, v20
	v_exp_f32_e32 v20, v20
	v_mul_f32_e32 v19, 0.5, v19
	v_lshlrev_b64 v[68:69], 8, v[34:35]
	v_lshlrev_b64 v[34:35], 8, v[42:43]
	v_add_f32_e32 v20, 1.0, v20
	v_rcp_f32_e32 v20, v20
	v_lshlrev_b64 v[42:43], 8, v[46:47]
	v_lshlrev_b64 v[46:47], 8, v[48:49]
	v_lshlrev_b64 v[48:49], 8, v[78:79]
	v_fma_f32 v20, v20, -2.0, 1.0
	v_add_f32_e32 v20, 1.0, v20
	v_mul_f32_e32 v73, v19, v20
	v_add_f32_e32 v19, v23, v0
	v_mul_f32_e32 v20, 0x3d372713, v19
	v_mul_f32_e32 v20, v19, v20
	v_fma_f32 v20, v19, v20, v19
	v_mul_f32_e32 v20, 0x3f4c422a, v20
	v_add_f32_e32 v20, v20, v20
	v_mul_f32_e32 v20, 0x3fb8aa3b, v20
	v_exp_f32_e32 v20, v20
	v_mul_f32_e32 v19, 0.5, v19
	v_cvt_pk_bf16_f32 v22, v70, s0
	v_lshlrev_b64 v[56:57], 8, v[56:57]
	v_add_f32_e32 v20, 1.0, v20
	v_rcp_f32_e32 v20, v20
	v_lshl_add_u64 v[34:35], v[66:67], 0, v[34:35]
	v_lshl_add_u64 v[36:37], v[66:67], 0, v[36:37]
	v_lshl_add_u64 v[38:39], v[66:67], 0, v[38:39]
	v_fma_f32 v20, v20, -2.0, 1.0
	v_add_f32_e32 v20, 1.0, v20
	v_mul_f32_e32 v74, v19, v20
	v_add_f32_e32 v19, v24, v0
	v_mul_f32_e32 v20, 0x3d372713, v19
	v_mul_f32_e32 v20, v19, v20
	v_fma_f32 v20, v19, v20, v19
	v_mul_f32_e32 v20, 0x3f4c422a, v20
	v_add_f32_e32 v20, v20, v20
	v_mul_f32_e32 v20, 0x3fb8aa3b, v20
	v_exp_f32_e32 v20, v20
	v_mul_f32_e32 v19, 0.5, v19
	v_cvt_pk_bf16_f32 v24, v71, s0
	v_lshl_add_u64 v[40:41], v[66:67], 0, v[40:41]
	v_add_f32_e32 v20, 1.0, v20
	v_rcp_f32_e32 v20, v20
	v_lshl_add_u64 v[42:43], v[66:67], 0, v[42:43]
	v_lshl_add_u64 v[44:45], v[66:67], 0, v[44:45]
	v_lshl_add_u64 v[48:49], v[66:67], 0, v[48:49]
	v_fma_f32 v20, v20, -2.0, 1.0
	v_add_f32_e32 v20, 1.0, v20
	v_mul_f32_e32 v75, v19, v20
	v_add_f32_e32 v19, v25, v0
	v_mul_f32_e32 v20, 0x3d372713, v19
	v_mul_f32_e32 v20, v19, v20
	v_fma_f32 v20, v19, v20, v19
	v_mul_f32_e32 v20, 0x3f4c422a, v20
	v_add_f32_e32 v20, v20, v20
	v_mul_f32_e32 v20, 0x3fb8aa3b, v20
	v_exp_f32_e32 v20, v20
	v_mul_f32_e32 v19, 0.5, v19
	v_lshl_add_u64 v[46:47], v[66:67], 0, v[46:47]
	v_add_f32_e32 v20, 1.0, v20
	v_rcp_f32_e32 v20, v20
	s_nop 0
	v_fma_f32 v20, v20, -2.0, 1.0
	v_add_f32_e32 v20, 1.0, v20
	v_mul_f32_e32 v76, v19, v20
	v_add_f32_e32 v19, v26, v0
	v_mul_f32_e32 v20, 0x3d372713, v19
	v_mul_f32_e32 v20, v19, v20
	v_fma_f32 v20, v19, v20, v19
	v_mul_f32_e32 v20, 0x3f4c422a, v20
	v_add_f32_e32 v20, v20, v20
	v_mul_f32_e32 v20, 0x3fb8aa3b, v20
	v_exp_f32_e32 v20, v20
	v_mul_f32_e32 v19, 0.5, v19
	v_cvt_pk_bf16_f32 v26, v72, s0
	v_add_f32_e32 v20, 1.0, v20
	v_rcp_f32_e32 v20, v20
	s_nop 0
	v_fma_f32 v20, v20, -2.0, 1.0
	v_add_f32_e32 v20, 1.0, v20
	v_mul_f32_e32 v77, v19, v20
	v_add_f32_e32 v19, v27, v0
	v_mul_f32_e32 v20, 0x3d372713, v19
	v_mul_f32_e32 v20, v19, v20
	v_fma_f32 v20, v19, v20, v19
	v_mul_f32_e32 v20, 0x3f4c422a, v20
	v_add_f32_e32 v20, v20, v20
	v_mul_f32_e32 v20, 0x3fb8aa3b, v20
	v_exp_f32_e32 v20, v20
	v_mul_f32_e32 v19, 0.5, v19
	v_add_f32_e32 v20, 1.0, v20
	v_rcp_f32_e32 v20, v20
	s_nop 0
	v_fma_f32 v20, v20, -2.0, 1.0
	v_add_f32_e32 v20, 1.0, v20
	v_mul_f32_e32 v78, v19, v20
	v_add_f32_e32 v19, v28, v0
	v_mul_f32_e32 v20, 0x3d372713, v19
	v_mul_f32_e32 v20, v19, v20
	v_fma_f32 v20, v19, v20, v19
	v_mul_f32_e32 v20, 0x3f4c422a, v20
	v_add_f32_e32 v20, v20, v20
	v_mul_f32_e32 v20, 0x3fb8aa3b, v20
	v_exp_f32_e32 v20, v20
	v_mul_f32_e32 v19, 0.5, v19
	v_cvt_pk_bf16_f32 v28, v73, s0
	v_add_f32_e32 v20, 1.0, v20
	v_rcp_f32_e32 v20, v20
	s_nop 0
	v_fma_f32 v20, v20, -2.0, 1.0
	v_add_f32_e32 v20, 1.0, v20
	v_mul_f32_e32 v79, v19, v20
	v_add_f32_e32 v19, v29, v0
	v_mul_f32_e32 v20, 0x3d372713, v19
	v_mul_f32_e32 v20, v19, v20
	v_fma_f32 v20, v19, v20, v19
	v_mul_f32_e32 v20, 0x3f4c422a, v20
	v_add_f32_e32 v20, v20, v20
	v_mul_f32_e32 v20, 0x3fb8aa3b, v20
	v_exp_f32_e32 v20, v20
	v_mul_f32_e32 v19, 0.5, v19
	v_add_f32_e32 v20, 1.0, v20
	v_rcp_f32_e32 v20, v20
	s_nop 0
	v_fma_f32 v20, v20, -2.0, 1.0
	v_add_f32_e32 v20, 1.0, v20
	v_mul_f32_e32 v80, v19, v20
	v_add_f32_e32 v19, v30, v0
	v_mul_f32_e32 v20, 0x3d372713, v19
	v_mul_f32_e32 v20, v19, v20
	v_fma_f32 v20, v19, v20, v19
	v_mul_f32_e32 v20, 0x3f4c422a, v20
	v_add_f32_e32 v20, v20, v20
	v_mul_f32_e32 v20, 0x3fb8aa3b, v20
	v_exp_f32_e32 v20, v20
	v_mul_f32_e32 v19, 0.5, v19
	v_cvt_pk_bf16_f32 v30, v74, s0
	v_add_f32_e32 v20, 1.0, v20
	v_rcp_f32_e32 v20, v20
	s_nop 0
	v_fma_f32 v20, v20, -2.0, 1.0
	v_add_f32_e32 v20, 1.0, v20
	v_mul_f32_e32 v81, v19, v20
	v_add_f32_e32 v19, v31, v0
	v_mul_f32_e32 v20, 0x3d372713, v19
	v_mul_f32_e32 v20, v19, v20
	v_fma_f32 v20, v19, v20, v19
	v_mul_f32_e32 v20, 0x3f4c422a, v20
	v_add_f32_e32 v20, v20, v20
	v_mul_f32_e32 v20, 0x3fb8aa3b, v20
	v_exp_f32_e32 v20, v20
	v_mul_f32_e32 v19, 0.5, v19
	v_add_f32_e32 v20, 1.0, v20
	v_rcp_f32_e32 v20, v20
	s_nop 0
	v_fma_f32 v20, v20, -2.0, 1.0
	v_add_f32_e32 v20, 1.0, v20
	v_mul_f32_e32 v82, v19, v20
	v_add_f32_e32 v19, v32, v0
	v_mul_f32_e32 v20, 0x3d372713, v19
	v_mul_f32_e32 v20, v19, v20
	v_fma_f32 v20, v19, v20, v19
	v_mul_f32_e32 v20, 0x3f4c422a, v20
	v_add_f32_e32 v20, v20, v20
	v_mul_f32_e32 v20, 0x3fb8aa3b, v20
	v_exp_f32_e32 v20, v20
	v_mul_f32_e32 v19, 0.5, v19
	v_add_f32_e32 v0, v33, v0
	v_cvt_pk_bf16_f32 v32, v75, s0
	v_add_f32_e32 v20, 1.0, v20
	v_rcp_f32_e32 v20, v20
	s_nop 0
	v_fma_f32 v20, v20, -2.0, 1.0
	v_add_f32_e32 v20, 1.0, v20
	v_mul_f32_e32 v83, v19, v20
	v_mul_f32_e32 v19, 0x3d372713, v0
	v_mul_f32_e32 v19, v0, v19
	v_fma_f32 v19, v0, v19, v0
	v_mul_f32_e32 v19, 0x3f4c422a, v19
	v_add_f32_e32 v19, v19, v19
	v_mul_f32_e32 v19, 0x3fb8aa3b, v19
	v_exp_f32_e32 v19, v19
	v_mul_f32_e32 v0, 0.5, v0
	v_cvt_pk_bf16_f32 v20, v18, s0
	v_add_f32_e32 v19, 1.0, v19
	v_rcp_f32_e32 v19, v19
	s_nop 0
	v_fma_f32 v19, v19, -2.0, 1.0
	v_add_f32_e32 v19, 1.0, v19
	v_mul_f32_e32 v0, v0, v19
	v_lshl_add_u64 v[18:19], v[66:67], 0, v[68:69]
	global_store_short v[18:19], v20, off
	v_lshl_add_u64 v[20:21], v[66:67], 0, v[64:65]
	global_store_short v[20:21], v22, off
	v_lshl_add_u64 v[22:23], v[66:67], 0, v[62:63]
	global_store_short v[22:23], v24, off
	v_lshl_add_u64 v[24:25], v[66:67], 0, v[60:61]
	global_store_short v[24:25], v26, off
	v_lshl_add_u64 v[26:27], v[66:67], 0, v[58:59]
	global_store_short v[26:27], v28, off
	v_lshl_add_u64 v[28:29], v[66:67], 0, v[56:57]
	global_store_short v[28:29], v30, off
	v_lshl_add_u64 v[30:31], v[66:67], 0, v[54:55]
	global_store_short v[30:31], v32, off
	v_lshl_add_u64 v[32:33], v[66:67], 0, v[52:53]
	v_cvt_pk_bf16_f32 v52, v77, s0
	global_store_short v[34:35], v52, off
	v_cvt_pk_bf16_f32 v52, v78, s0
	global_store_short v[36:37], v52, off
	v_cvt_pk_bf16_f32 v52, v79, s0
	global_store_short v[38:39], v52, off
	v_cvt_pk_bf16_f32 v52, v80, s0
	global_store_short v[40:41], v52, off
	v_cvt_pk_bf16_f32 v52, v81, s0
	global_store_short v[42:43], v52, off
	v_cvt_pk_bf16_f32 v52, v82, s0
	v_cvt_pk_bf16_f32 v0, v0, s0
	v_cvt_pk_bf16_f32 v54, v76, s0
	global_store_short v[44:45], v52, off
	v_cvt_pk_bf16_f32 v52, v83, s0
	global_store_short v[48:49], v0, off
	v_mov_b32_e32 v0, 0
	s_mov_b64 s[0:1], 0
	global_store_short v[32:33], v54, off
	global_store_short v[46:47], v52, off
.LBB0_629:
	v_lshl_add_u64 v[52:53], v[50:51], 0, s[0:1]
	s_add_u32 s0, s0, 0x1000
	s_addc_u32 s1, s1, 0
	s_cmpk_lg_i32 s0, 0x4000
	global_load_dword v192, v[52:53], off offset:-2048
	global_load_dword v193, v[52:53], off offset:-1536
	global_load_dword v194, v[52:53], off offset:-1024
	global_load_dword v195, v[52:53], off offset:-512
	global_load_dword v196, v[52:53], off
	global_load_dword v197, v[52:53], off offset:512
	global_load_dword v198, v[52:53], off offset:1024
	global_load_dword v199, v[52:53], off offset:1536
	s_waitcnt vmcnt(7)
	v_add_f32_e32 v0, v0, v192
	s_waitcnt vmcnt(6)
	v_add_f32_e32 v0, v0, v193
	s_waitcnt vmcnt(5)
	v_add_f32_e32 v0, v0, v194
	s_waitcnt vmcnt(4)
	v_add_f32_e32 v0, v0, v195
	s_waitcnt vmcnt(3)
	v_add_f32_e32 v0, v0, v196
	s_waitcnt vmcnt(2)
	v_add_f32_e32 v0, v0, v197
	s_waitcnt vmcnt(1)
	v_add_f32_e32 v0, v0, v198
	s_waitcnt vmcnt(0)
	v_add_f32_e32 v0, v0, v199
	s_cbranch_scc1 .LBB0_629
	v_add_f32_e32 v2, v2, v0
	v_mul_f32_e32 v50, 0x3d372713, v2
	v_mul_f32_e32 v50, v2, v50
	v_fma_f32 v50, v2, v50, v2
	v_mul_f32_e32 v50, 0x3f4c422a, v50
	v_add_f32_e32 v50, v50, v50
	v_mul_f32_e32 v50, 0x3fb8aa3b, v50
	v_exp_f32_e32 v50, v50
	v_mul_f32_e32 v2, 0.5, v2
	v_add_f32_e32 v3, v3, v0
	v_add_f32_e32 v4, v4, v0
	v_add_f32_e32 v50, 1.0, v50
	v_rcp_f32_e32 v50, v50
	v_add_f32_e32 v5, v5, v0
	v_add_f32_e32 v6, v6, v0
	v_add_f32_e32 v7, v7, v0
	v_fma_f32 v50, v50, -2.0, 1.0
	v_add_f32_e32 v50, 1.0, v50
	v_mul_f32_e32 v2, v2, v50
	v_mul_f32_e32 v50, 0x3d372713, v3
	v_mul_f32_e32 v50, v3, v50
	v_fma_f32 v50, v3, v50, v3
	v_mul_f32_e32 v50, 0x3f4c422a, v50
	v_add_f32_e32 v50, v50, v50
	v_mul_f32_e32 v50, 0x3fb8aa3b, v50
	v_exp_f32_e32 v50, v50
	v_mul_f32_e32 v3, 0.5, v3
	v_add_f32_e32 v8, v8, v0
	v_add_f32_e32 v9, v9, v0
	v_add_f32_e32 v50, 1.0, v50
	v_rcp_f32_e32 v50, v50
	v_add_f32_e32 v10, v10, v0
	v_add_f32_e32 v11, v11, v0
	v_add_f32_e32 v12, v12, v0
	v_fma_f32 v50, v50, -2.0, 1.0
	v_add_f32_e32 v50, 1.0, v50
	v_mul_f32_e32 v3, v3, v50
	v_mul_f32_e32 v50, 0x3d372713, v4
	v_mul_f32_e32 v50, v4, v50
	v_fma_f32 v50, v4, v50, v4
	v_mul_f32_e32 v50, 0x3f4c422a, v50
	v_add_f32_e32 v50, v50, v50
	v_mul_f32_e32 v50, 0x3fb8aa3b, v50
	v_exp_f32_e32 v50, v50
	v_mul_f32_e32 v4, 0.5, v4
	v_add_f32_e32 v13, v13, v0
	v_add_f32_e32 v14, v14, v0
	v_add_f32_e32 v50, 1.0, v50
	v_rcp_f32_e32 v50, v50
	v_add_f32_e32 v15, v15, v0
	v_add_f32_e32 v16, v16, v0
	v_add_f32_e32 v0, v17, v0
	v_fma_f32 v50, v50, -2.0, 1.0
	v_add_f32_e32 v50, 1.0, v50
	v_mul_f32_e32 v4, v4, v50
	v_mul_f32_e32 v50, 0x3d372713, v5
	v_mul_f32_e32 v50, v5, v50
	v_fma_f32 v50, v5, v50, v5
	v_mul_f32_e32 v50, 0x3f4c422a, v50
	v_add_f32_e32 v50, v50, v50
	v_mul_f32_e32 v50, 0x3fb8aa3b, v50
	v_exp_f32_e32 v50, v50
	v_mul_f32_e32 v5, 0.5, v5
	v_mul_f32_e32 v17, 0x3d372713, v0
	v_mul_f32_e32 v17, v0, v17
	v_add_f32_e32 v50, 1.0, v50
	v_rcp_f32_e32 v50, v50
	v_fma_f32 v17, v0, v17, v0
	v_mul_f32_e32 v17, 0x3f4c422a, v17
	v_add_f32_e32 v17, v17, v17
	v_fma_f32 v50, v50, -2.0, 1.0
	v_add_f32_e32 v50, 1.0, v50
	v_mul_f32_e32 v5, v5, v50
	v_mul_f32_e32 v50, 0x3d372713, v6
	v_mul_f32_e32 v50, v6, v50
	v_fma_f32 v50, v6, v50, v6
	v_mul_f32_e32 v50, 0x3f4c422a, v50
	v_add_f32_e32 v50, v50, v50
	v_mul_f32_e32 v50, 0x3fb8aa3b, v50
	v_exp_f32_e32 v50, v50
	v_mul_f32_e32 v6, 0.5, v6
	v_cvt_pk_bf16_f32 v2, v2, s0
	v_mul_f32_e32 v17, 0x3fb8aa3b, v17
	v_add_f32_e32 v50, 1.0, v50
	v_rcp_f32_e32 v50, v50
	global_store_short v[18:19], v2, off offset:64
	v_cvt_pk_bf16_f32 v2, v3, s0
	v_exp_f32_e32 v17, v17
	v_fma_f32 v50, v50, -2.0, 1.0
	v_add_f32_e32 v50, 1.0, v50
	v_mul_f32_e32 v6, v6, v50
	v_mul_f32_e32 v50, 0x3d372713, v7
	v_mul_f32_e32 v50, v7, v50
	v_fma_f32 v50, v7, v50, v7
	v_mul_f32_e32 v50, 0x3f4c422a, v50
	v_add_f32_e32 v50, v50, v50
	v_mul_f32_e32 v50, 0x3fb8aa3b, v50
	v_exp_f32_e32 v50, v50
	v_mul_f32_e32 v7, 0.5, v7
	global_store_short v[20:21], v2, off offset:64
	v_cvt_pk_bf16_f32 v2, v4, s0
	v_add_f32_e32 v50, 1.0, v50
	v_rcp_f32_e32 v50, v50
	global_store_short v[22:23], v2, off offset:64
	v_cvt_pk_bf16_f32 v2, v5, s0
	global_store_short v[24:25], v2, off offset:64
	v_fma_f32 v50, v50, -2.0, 1.0
	v_add_f32_e32 v50, 1.0, v50
	v_mul_f32_e32 v7, v7, v50
	v_mul_f32_e32 v50, 0x3d372713, v8
	v_mul_f32_e32 v50, v8, v50
	v_fma_f32 v50, v8, v50, v8
	v_mul_f32_e32 v50, 0x3f4c422a, v50
	v_add_f32_e32 v50, v50, v50
	v_mul_f32_e32 v50, 0x3fb8aa3b, v50
	v_exp_f32_e32 v50, v50
	v_mul_f32_e32 v8, 0.5, v8
	v_cvt_pk_bf16_f32 v2, v6, s0
	global_store_short v[26:27], v2, off offset:64
	v_add_f32_e32 v50, 1.0, v50
	v_rcp_f32_e32 v50, v50
	v_cvt_pk_bf16_f32 v2, v7, s0
	v_add_f32_e32 v17, 1.0, v17
	global_store_short v[28:29], v2, off offset:64
	v_fma_f32 v50, v50, -2.0, 1.0
	v_add_f32_e32 v50, 1.0, v50
	v_mul_f32_e32 v8, v8, v50
	v_mul_f32_e32 v50, 0x3d372713, v9
	v_mul_f32_e32 v50, v9, v50
	v_fma_f32 v50, v9, v50, v9
	v_mul_f32_e32 v50, 0x3f4c422a, v50
	v_add_f32_e32 v50, v50, v50
	v_mul_f32_e32 v50, 0x3fb8aa3b, v50
	v_exp_f32_e32 v50, v50
	v_mul_f32_e32 v9, 0.5, v9
	v_cvt_pk_bf16_f32 v2, v8, s0
	v_rcp_f32_e32 v17, v17
	v_add_f32_e32 v50, 1.0, v50
	v_rcp_f32_e32 v50, v50
	global_store_short v[30:31], v2, off offset:64
	v_fma_f32 v17, v17, -2.0, 1.0
	v_mul_f32_e32 v0, 0.5, v0
	v_fma_f32 v50, v50, -2.0, 1.0
	v_add_f32_e32 v50, 1.0, v50
	v_mul_f32_e32 v9, v9, v50
	v_mul_f32_e32 v50, 0x3d372713, v10
	v_mul_f32_e32 v50, v10, v50
	v_fma_f32 v50, v10, v50, v10
	v_mul_f32_e32 v50, 0x3f4c422a, v50
	v_add_f32_e32 v50, v50, v50
	v_mul_f32_e32 v50, 0x3fb8aa3b, v50
	v_exp_f32_e32 v50, v50
	v_mul_f32_e32 v10, 0.5, v10
	v_cvt_pk_bf16_f32 v2, v9, s0
	global_store_short v[32:33], v2, off offset:64
	v_add_f32_e32 v50, 1.0, v50
	v_rcp_f32_e32 v50, v50
	v_add_f32_e32 v17, 1.0, v17
	v_mul_f32_e32 v0, v0, v17
	v_cvt_pk_bf16_f32 v0, v0, s0
	v_fma_f32 v50, v50, -2.0, 1.0
	v_add_f32_e32 v50, 1.0, v50
	v_mul_f32_e32 v10, v10, v50
	v_mul_f32_e32 v50, 0x3d372713, v11
	v_mul_f32_e32 v50, v11, v50
	v_fma_f32 v50, v11, v50, v11
	v_mul_f32_e32 v50, 0x3f4c422a, v50
	v_add_f32_e32 v50, v50, v50
	v_mul_f32_e32 v50, 0x3fb8aa3b, v50
	v_exp_f32_e32 v50, v50
	v_mul_f32_e32 v11, 0.5, v11
	v_cvt_pk_bf16_f32 v2, v10, s0
	global_store_short v[34:35], v2, off offset:64
	v_add_f32_e32 v50, 1.0, v50
	v_rcp_f32_e32 v50, v50
	global_store_short v[48:49], v0, off offset:64
	v_fma_f32 v50, v50, -2.0, 1.0
	v_add_f32_e32 v50, 1.0, v50
	v_mul_f32_e32 v11, v11, v50
	v_mul_f32_e32 v50, 0x3d372713, v12
	v_mul_f32_e32 v50, v12, v50
	v_fma_f32 v50, v12, v50, v12
	v_mul_f32_e32 v50, 0x3f4c422a, v50
	v_add_f32_e32 v50, v50, v50
	v_mul_f32_e32 v50, 0x3fb8aa3b, v50
	v_exp_f32_e32 v50, v50
	v_mul_f32_e32 v12, 0.5, v12
	v_cvt_pk_bf16_f32 v2, v11, s0
	global_store_short v[36:37], v2, off offset:64
	v_add_f32_e32 v50, 1.0, v50
	v_rcp_f32_e32 v50, v50
	s_nop 0
	v_fma_f32 v50, v50, -2.0, 1.0
	v_add_f32_e32 v50, 1.0, v50
	v_mul_f32_e32 v12, v12, v50
	v_mul_f32_e32 v50, 0x3d372713, v13
	v_mul_f32_e32 v50, v13, v50
	v_fma_f32 v50, v13, v50, v13
	v_mul_f32_e32 v50, 0x3f4c422a, v50
	v_add_f32_e32 v50, v50, v50
	v_mul_f32_e32 v50, 0x3fb8aa3b, v50
	v_exp_f32_e32 v50, v50
	v_mul_f32_e32 v13, 0.5, v13
	v_cvt_pk_bf16_f32 v2, v12, s0
	global_store_short v[38:39], v2, off offset:64
	v_add_f32_e32 v50, 1.0, v50
	v_rcp_f32_e32 v50, v50
	s_nop 0
	v_fma_f32 v50, v50, -2.0, 1.0
	v_add_f32_e32 v50, 1.0, v50
	v_mul_f32_e32 v13, v13, v50
	v_mul_f32_e32 v50, 0x3d372713, v14
	v_mul_f32_e32 v50, v14, v50
	v_fma_f32 v50, v14, v50, v14
	v_mul_f32_e32 v50, 0x3f4c422a, v50
	v_add_f32_e32 v50, v50, v50
	v_mul_f32_e32 v50, 0x3fb8aa3b, v50
	v_exp_f32_e32 v50, v50
	v_mul_f32_e32 v14, 0.5, v14
	v_cvt_pk_bf16_f32 v2, v13, s0
	global_store_short v[40:41], v2, off offset:64
	v_add_f32_e32 v50, 1.0, v50
	v_rcp_f32_e32 v50, v50
	s_nop 0
	v_fma_f32 v50, v50, -2.0, 1.0
	v_add_f32_e32 v50, 1.0, v50
	v_mul_f32_e32 v14, v14, v50
	v_mul_f32_e32 v50, 0x3d372713, v15
	v_mul_f32_e32 v50, v15, v50
	v_fma_f32 v50, v15, v50, v15
	v_mul_f32_e32 v50, 0x3f4c422a, v50
	v_add_f32_e32 v50, v50, v50
	v_mul_f32_e32 v50, 0x3fb8aa3b, v50
	v_exp_f32_e32 v50, v50
	v_mul_f32_e32 v15, 0.5, v15
	v_cvt_pk_bf16_f32 v2, v14, s0
	global_store_short v[42:43], v2, off offset:64
	v_add_f32_e32 v50, 1.0, v50
	v_rcp_f32_e32 v50, v50
	s_nop 0
	v_fma_f32 v50, v50, -2.0, 1.0
	v_add_f32_e32 v50, 1.0, v50
	v_mul_f32_e32 v15, v15, v50
	v_mul_f32_e32 v50, 0x3d372713, v16
	v_mul_f32_e32 v50, v16, v50
	v_fma_f32 v50, v16, v50, v16
	v_mul_f32_e32 v50, 0x3f4c422a, v50
	v_add_f32_e32 v50, v50, v50
	v_mul_f32_e32 v50, 0x3fb8aa3b, v50
	v_exp_f32_e32 v50, v50
	v_mul_f32_e32 v16, 0.5, v16
	v_cvt_pk_bf16_f32 v2, v15, s0
	global_store_short v[44:45], v2, off offset:64
	v_add_f32_e32 v50, 1.0, v50
	v_rcp_f32_e32 v50, v50
	s_nop 0
	v_fma_f32 v50, v50, -2.0, 1.0
	v_add_f32_e32 v50, 1.0, v50
	v_mul_f32_e32 v16, v16, v50
	v_cvt_pk_bf16_f32 v2, v16, s0
	global_store_short v[46:47], v2, off offset:64
	s_branch .LBB0_505
